# plus multi-unit GEMM phases: first K-loop trip peeled with inline-0 accumulator input, accumulator zeroing removed
# speedup vs baseline: 1.0035x; 1.0035x over previous
; #define PG8_STAGE(bufoff, gbase, voff) do { _Pragma("unroll") for (int _i = 0; _i < 2; ++_i) \
;         __builtin_amdgcn_global_load_lds((const unsigned*)((const char*)(gbase) + (voff)[_i]), (PG8_LAS unsigned*)(lds + (bufoff) + ldsw + _i * 8192), 16, 0, 0); } while (0)
; #define PG8_LDA(dst, b, h) do { _Pragma("unroll") for (int m = 0; m < 4; ++m) _Pragma("unroll") for (int k = 0; k < 2; ++k) dst[m][k] = *(const PG8_LAS bf16x8*)(lds + PG8_SA(b, h) + aoff + m * 2048 + k * 1024); } while (0)
; #define PG8_LDB(dst, b, h) do { _Pragma("unroll") for (int n = 0; n < 2; ++n) _Pragma("unroll") for (int k = 0; k < 2; ++k) dst[n][k] = *(const PG8_LAS bf16x8*)(lds + PG8_SB(b, h) + boff + n * 2048 + k * 1024); } while (0)
; #define PG8_WAIT_V(n) asm volatile("s_waitcnt vmcnt(" #n ")" ::: "memory")
; #define PG8_WAIT_L(n) asm volatile("s_waitcnt lgkmcnt(" #n ")" ::: "memory")
; #define PG8_BAR __builtin_amdgcn_s_barrier()
; #define PG8_SCHED __builtin_amdgcn_sched_barrier(0)
; template <class Epi, class Sched, bool ALIGN_EPI = false, bool SP2 = false>
; __device__ __forceinline__ void gemm_phase(PG8_LAS unsigned char* lds, const Gemm g, const Sched& S, const Epi& E) {
;     ...
;         const bool has_next = S.next(ui + 1, nxt);
;         const char* nA = has_next ? (const char*)g.A + (size_t)nxt.pm * tstep : cA; const char* nB = has_next ? (const char*)g.Bt + (size_t)nxt.pn * tstep : cB;
;         for (int t = 0; t < nt; t += 2) {
;             const bool last = (t == nt - 2);
;             const char* a1 = cA + (size_t)(t + 1) * kstep;
;             const char* a2 = last ? nA : cA + (size_t)(t + 2) * kstep; const char* b2 = last ? nB : cB + (size_t)(t + 2) * kstep;
;             const char* a3 = a2 + kstep; const char* b3 = b2 + kstep;
;             if (last && has_next) S.a_ready(nxt);
;             if constexpr (SP2) {
;             PG8_LDB(B0, 0, 0); PG8_LDB(B1, 0, 1); PG8_SCHED; PG8_LDA(At, 0, 0); PG8_STAGE(PG8_SA(1, 1), a1 + hstep, voffA);
;             PG8_WAIT_V(8); PG8_WAIT_L(0); PG8_BAR; PG8_MMA(0, 0, At, B0); PG8_MMA(0, 1, At, B1); PG8_BAR; PG8_SCHED;
;             PG8_LDA(At, 0, 1); PG8_STAGE(PG8_SB(0, 0), b2, voffB); PG8_STAGE(PG8_SB(0, 1), b2 + hstep, voffB); PG8_STAGE(PG8_SA(0, 0), a2, voffA);
;             PG8_WAIT_V(8); PG8_WAIT_L(0); PG8_BAR; PG8_MMA(1, 0, At, B0); PG8_MMA(1, 1, At, B1); PG8_BAR; PG8_SCHED;
.LBB0_142:
	s_ashr_i32 s29, s28, 31
	s_lshl_b64 s[30:31], s[28:29], 19
	s_add_u32 s30, s54, s30
	s_addc_u32 s31, s55, s31
	s_and_b64 s[34:35], s[4:5], exec
	s_cselect_b32 s7, s31, s39
	s_cselect_b32 s29, s30, s38
	s_ashr_i32 s27, s26, 31
	s_lshl_b64 s[34:35], s[26:27], 19
	s_add_u32 s34, s62, s34
	s_addc_u32 s35, s63, s35
	s_and_b64 s[42:43], s[4:5], exec
	s_cselect_b32 s27, s35, s41
	s_cselect_b32 s82, s34, s40
	s_add_u32 s38, s38, 0x40080
	s_addc_u32 s39, s39, 0
	s_add_u32 s83, s40, 0x100
	v_mov_b32_e32 v0, 0
	s_addc_u32 s84, s41, 0
	s_mov_b32 s85, -2
	v_mov_b32_e32 v1, v0
	ds_read_b128 v[144:147], v163
	ds_read_b128 v[168:171], v163 offset:1024
	ds_read_b128 v[172:175], v163 offset:2048
	ds_read_b128 v[176:179], v163 offset:3072
	ds_read_b128 v[180:183], v164
	ds_read_b128 v[184:187], v164 offset:1024
	ds_read_b128 v[188:191], v164 offset:2048
	ds_read_b128 v[192:195], v164 offset:3072
	s_add_u32 s40, s38, 0xfffc0080
	s_addc_u32 s41, s39, -1
	s_cmp_eq_u32 s85, 12
	s_cselect_b32 s43, s7, s41
	s_cselect_b32 s42, s29, s40
	s_cselect_b32 s41, s27, s84
	s_cselect_b32 s40, s82, s83
	v_lshl_add_u64 v[148:149], s[38:39], 0, v[136:137]
	s_add_i32 m0, s37, 0xc000
	ds_read_b128 v[196:199], v165
	ds_read_b128 v[200:203], v165 offset:1024
	ds_read_b128 v[204:207], v165 offset:2048
	ds_read_b128 v[210:213], v165 offset:3072
	ds_read_b128 v[214:217], v165 offset:4096
	ds_read_b128 v[218:221], v165 offset:5120
	ds_read_b128 v[222:225], v165 offset:6144
	ds_read_b128 v[226:229], v165 offset:7168
	global_load_lds_dwordx4 v[148:149], off
	v_lshl_add_u64 v[148:149], s[38:39], 0, v[138:139]
	s_add_i32 m0, s37, 0xe000
	s_nop 0
	global_load_lds_dwordx4 v[148:149], off
	s_waitcnt vmcnt(8)
	s_waitcnt lgkmcnt(0)
	s_barrier
	s_setprio 1
	s_waitcnt lgkmcnt(0)
	v_mfma_f32_16x16x32_bf16 v[124:127], v[144:147], v[196:199], 0
	v_mfma_f32_16x16x32_bf16 v[116:119], v[172:175], v[196:199], 0
	v_mfma_f32_16x16x32_bf16 v[108:111], v[144:147], v[204:207], 0
	v_mfma_f32_16x16x32_bf16 v[100:103], v[172:175], v[204:207], 0
	v_mfma_f32_16x16x32_bf16 v[92:95], v[144:147], v[214:217], 0
	v_mfma_f32_16x16x32_bf16 v[84:87], v[172:175], v[214:217], 0
	v_mfma_f32_16x16x32_bf16 v[76:79], v[144:147], v[222:225], 0
	v_mfma_f32_16x16x32_bf16 v[68:71], v[172:175], v[222:225], 0
	v_mfma_f32_16x16x32_bf16 v[124:127], v[168:171], v[200:203], v[124:127]
	v_mfma_f32_16x16x32_bf16 v[116:119], v[176:179], v[200:203], v[116:119]
	v_mfma_f32_16x16x32_bf16 v[108:111], v[168:171], v[210:213], v[108:111]
	v_mfma_f32_16x16x32_bf16 v[100:103], v[176:179], v[210:213], v[100:103]
	v_mfma_f32_16x16x32_bf16 v[92:95], v[168:171], v[218:221], v[92:95]
	v_mfma_f32_16x16x32_bf16 v[84:87], v[176:179], v[218:221], v[84:87]
	v_mfma_f32_16x16x32_bf16 v[76:79], v[168:171], v[226:229], v[76:79]
	v_mfma_f32_16x16x32_bf16 v[68:71], v[176:179], v[226:229], v[68:71]
	s_setprio 0
	s_setprio 1
	v_mfma_f32_16x16x32_bf16 v[120:123], v[180:183], v[196:199], 0
	v_mfma_f32_16x16x32_bf16 v[112:115], v[188:191], v[196:199], 0
	v_mfma_f32_16x16x32_bf16 v[104:107], v[180:183], v[204:207], 0
	v_mfma_f32_16x16x32_bf16 v[96:99], v[188:191], v[204:207], 0
	v_mfma_f32_16x16x32_bf16 v[88:91], v[180:183], v[214:217], 0
	v_mfma_f32_16x16x32_bf16 v[80:83], v[188:191], v[214:217], 0
	v_mfma_f32_16x16x32_bf16 v[72:75], v[180:183], v[222:225], 0
	v_mfma_f32_16x16x32_bf16 v[64:67], v[188:191], v[222:225], 0
	v_mfma_f32_16x16x32_bf16 v[120:123], v[184:187], v[200:203], v[120:123]
	v_mfma_f32_16x16x32_bf16 v[112:115], v[192:195], v[200:203], v[112:115]
	v_mfma_f32_16x16x32_bf16 v[104:107], v[184:187], v[210:213], v[104:107]
	v_mfma_f32_16x16x32_bf16 v[96:99], v[192:195], v[210:213], v[96:99]
	v_mfma_f32_16x16x32_bf16 v[88:91], v[184:187], v[218:221], v[88:91]
	v_mfma_f32_16x16x32_bf16 v[80:83], v[192:195], v[218:221], v[80:83]
	v_mfma_f32_16x16x32_bf16 v[72:75], v[184:187], v[226:229], v[72:75]
	s_barrier
	v_mfma_f32_16x16x32_bf16 v[64:67], v[192:195], v[226:229], v[64:67]
	s_setprio 0
	s_add_i32 s52, s77, s64
	v_lshl_add_u64 v[148:149], s[40:41], 0, v[130:131]
	s_mov_b32 m0, s52
	ds_read_b128 v[196:199], v165 offset:16384
	ds_read_b128 v[200:203], v165 offset:17408
	ds_read_b128 v[204:207], v165 offset:18432
	ds_read_b128 v[210:213], v165 offset:19456
	ds_read_b128 v[214:217], v165 offset:20480
	ds_read_b128 v[218:221], v165 offset:21504
	ds_read_b128 v[222:225], v165 offset:22528
	ds_read_b128 v[226:229], v165 offset:23552
	global_load_lds_dwordx4 v[148:149], off
	s_add_i32 m0, s52, 0x2000
	s_add_u32 s86, s40, 0x40000
	v_lshl_add_u64 v[230:231], s[40:41], 0, v[134:135]
	s_addc_u32 s87, s41, 0
	s_add_i32 s52, s79, s64
	global_load_lds_dwordx4 v[230:231], off
	v_lshl_add_u64 v[232:233], s[86:87], 0, v[130:131]
	s_mov_b32 m0, s52
	v_lshl_add_u64 v[234:235], s[42:43], 0, v[132:133]
	global_load_lds_dwordx4 v[232:233], off
	v_lshl_add_u64 v[232:233], s[86:87], 0, v[134:135]
	s_add_i32 m0, s52, 0x2000
	s_nop 0
	global_load_lds_dwordx4 v[232:233], off
	v_lshl_add_u64 v[232:233], s[42:43], 0, v[128:129]
	s_mov_b32 m0, s37
	s_nop 0
	global_load_lds_dwordx4 v[232:233], off
	s_mov_b32 m0, s65
	s_nop 0
	global_load_lds_dwordx4 v[234:235], off
	s_waitcnt vmcnt(8)
	s_waitcnt lgkmcnt(0)
	s_barrier
; #define PG8_STAGE(bufoff, gbase, voff) do { _Pragma("unroll") for (int _i = 0; _i < 2; ++_i) \
;         __builtin_amdgcn_global_load_lds((const unsigned*)((const char*)(gbase) + (voff)[_i]), (PG8_LAS unsigned*)(lds + (bufoff) + ldsw + _i * 8192), 16, 0, 0); } while (0)
; #define PG8_LDA(dst, b, h) do { _Pragma("unroll") for (int m = 0; m < 4; ++m) _Pragma("unroll") for (int k = 0; k < 2; ++k) dst[m][k] = *(const PG8_LAS bf16x8*)(lds + PG8_SA(b, h) + aoff + m * 2048 + k * 1024); } while (0)
; #define PG8_LDB(dst, b, h) do { _Pragma("unroll") for (int n = 0; n < 2; ++n) _Pragma("unroll") for (int k = 0; k < 2; ++k) dst[n][k] = *(const PG8_LAS bf16x8*)(lds + PG8_SB(b, h) + boff + n * 2048 + k * 1024); } while (0)
; #define PG8_MMA(ai, bj, At, Bt) do { __builtin_amdgcn_s_setprio(1); _Pragma("unroll") for (int m = 0; m < 4; ++m) _Pragma("unroll") for (int n = 0; n < 2; ++n) _Pragma("unroll") for (int k = 0; k < 2; ++k) \
;         acc[ai][bj][m][n] = __builtin_amdgcn_mfma_f32_16x16x32_bf16(Bt[n][k], At[m][k], acc[ai][bj][m][n], 0, 0, 0); __builtin_amdgcn_s_setprio(0); } while (0)
; #define PG8_WAIT_V(n) asm volatile("s_waitcnt vmcnt(" #n ")" ::: "memory")
; #define PG8_WAIT_L(n) asm volatile("s_waitcnt lgkmcnt(" #n ")" ::: "memory")
; #define PG8_BAR __builtin_amdgcn_s_barrier()
; #define PG8_SCHED __builtin_amdgcn_sched_barrier(0)
; template <class Epi, class Sched, bool ALIGN_EPI = false, bool SP2 = false>
; __device__ __forceinline__ void gemm_phase(PG8_LAS unsigned char* lds, const Gemm g, const Sched& S, const Epi& E) {
;     ...
;             PG8_WAIT_V(8); PG8_WAIT_L(0); PG8_BAR; PG8_MMA(0, 0, At, B0); PG8_MMA(0, 1, At, B1); PG8_BAR; PG8_SCHED;
;             PG8_LDA(At, 0, 1); PG8_STAGE(PG8_SB(0, 0), b2, voffB); PG8_STAGE(PG8_SB(0, 1), b2 + hstep, voffB); PG8_STAGE(PG8_SA(0, 0), a2, voffA);
;             PG8_WAIT_V(8); PG8_WAIT_L(0); PG8_BAR; PG8_MMA(1, 0, At, B0); PG8_MMA(1, 1, At, B1); PG8_BAR; PG8_SCHED;
;             PG8_LDB(B0, 1, 0); PG8_LDB(B1, 1, 1); PG8_SCHED; PG8_LDA(At, 1, 0); PG8_STAGE(PG8_SA(0, 1), a2 + hstep, voffA);
;             PG8_WAIT_V(8); PG8_WAIT_L(0); PG8_BAR; PG8_MMA(0, 0, At, B0); PG8_MMA(0, 1, At, B1); PG8_BAR; PG8_SCHED;
	s_setprio 1
	s_waitcnt lgkmcnt(0)
	v_mfma_f32_16x16x32_bf16 v[60:63], v[144:147], v[196:199], 0
	v_mfma_f32_16x16x32_bf16 v[52:55], v[172:175], v[196:199], 0
	v_mfma_f32_16x16x32_bf16 v[44:47], v[144:147], v[204:207], 0
	v_mfma_f32_16x16x32_bf16 v[36:39], v[172:175], v[204:207], 0
	v_mfma_f32_16x16x32_bf16 v[28:31], v[144:147], v[214:217], 0
	v_mfma_f32_16x16x32_bf16 v[20:23], v[172:175], v[214:217], 0
	v_mfma_f32_16x16x32_bf16 v[12:15], v[144:147], v[222:225], 0
	v_mfma_f32_16x16x32_bf16 v[4:7], v[172:175], v[222:225], 0
	v_mfma_f32_16x16x32_bf16 v[60:63], v[168:171], v[200:203], v[60:63]
	v_mfma_f32_16x16x32_bf16 v[52:55], v[176:179], v[200:203], v[52:55]
	v_mfma_f32_16x16x32_bf16 v[44:47], v[168:171], v[210:213], v[44:47]
	v_mfma_f32_16x16x32_bf16 v[36:39], v[176:179], v[210:213], v[36:39]
	v_mfma_f32_16x16x32_bf16 v[28:31], v[168:171], v[218:221], v[28:31]
	v_mfma_f32_16x16x32_bf16 v[20:23], v[176:179], v[218:221], v[20:23]
	v_mfma_f32_16x16x32_bf16 v[12:15], v[168:171], v[226:229], v[12:15]
	v_mfma_f32_16x16x32_bf16 v[4:7], v[176:179], v[226:229], v[4:7]
	s_setprio 0
	s_setprio 1
	v_mfma_f32_16x16x32_bf16 v[56:59], v[180:183], v[196:199], 0
	v_mfma_f32_16x16x32_bf16 v[48:51], v[188:191], v[196:199], 0
	v_mfma_f32_16x16x32_bf16 v[40:43], v[180:183], v[204:207], 0
	v_mfma_f32_16x16x32_bf16 v[32:35], v[188:191], v[204:207], 0
	v_mfma_f32_16x16x32_bf16 v[24:27], v[180:183], v[214:217], 0
	v_mfma_f32_16x16x32_bf16 v[16:19], v[188:191], v[214:217], 0
	v_mfma_f32_16x16x32_bf16 v[8:11], v[180:183], v[222:225], 0
	v_mfma_f32_16x16x32_bf16 v[0:3], v[188:191], v[222:225], 0
	v_mfma_f32_16x16x32_bf16 v[56:59], v[184:187], v[200:203], v[56:59]
	v_mfma_f32_16x16x32_bf16 v[48:51], v[192:195], v[200:203], v[48:51]
	v_mfma_f32_16x16x32_bf16 v[40:43], v[184:187], v[210:213], v[40:43]
	v_mfma_f32_16x16x32_bf16 v[32:35], v[192:195], v[210:213], v[32:35]
	v_mfma_f32_16x16x32_bf16 v[24:27], v[184:187], v[218:221], v[24:27]
	v_mfma_f32_16x16x32_bf16 v[16:19], v[192:195], v[218:221], v[16:19]
	v_mfma_f32_16x16x32_bf16 v[8:11], v[184:187], v[226:229], v[8:11]
	s_barrier
	v_mfma_f32_16x16x32_bf16 v[0:3], v[192:195], v[226:229], v[0:3]
	s_setprio 0
	s_add_i32 s52, 0, 0x18000
	v_add_u32_e32 v150, s52, v161
	s_add_i32 s53, 0, 0x1c000
	ds_read_b128 v[144:147], v150
	ds_read_b128 v[168:171], v150 offset:1024
	ds_read_b128 v[172:175], v150 offset:2048
	ds_read_b128 v[176:179], v150 offset:3072
	v_add_u32_e32 v150, s53, v161
	ds_read_b128 v[180:183], v150
	ds_read_b128 v[184:187], v150 offset:1024
	ds_read_b128 v[188:191], v150 offset:2048
	ds_read_b128 v[192:195], v150 offset:3072
	s_add_u32 s42, s42, 0x40000
	s_addc_u32 s43, s43, 0
	s_mov_b32 m0, s66
	v_lshl_add_u64 v[236:237], s[42:43], 0, v[128:129]
	ds_read_b128 v[196:199], v165 offset:32768
	ds_read_b128 v[200:203], v165 offset:33792
	ds_read_b128 v[204:207], v165 offset:34816
	ds_read_b128 v[210:213], v165 offset:35840
	ds_read_b128 v[214:217], v165 offset:36864
	ds_read_b128 v[218:221], v165 offset:37888
	ds_read_b128 v[222:225], v165 offset:38912
	ds_read_b128 v[226:229], v165 offset:39936
	global_load_lds_dwordx4 v[236:237], off
	v_lshl_add_u64 v[236:237], s[42:43], 0, v[132:133]
	s_mov_b32 m0, s67
	s_nop 0
	global_load_lds_dwordx4 v[236:237], off
	s_waitcnt vmcnt(8)
	s_waitcnt lgkmcnt(0)
	s_barrier
	s_setprio 1
	s_waitcnt lgkmcnt(0)
	v_mfma_f32_16x16x32_bf16 v[124:127], v[144:147], v[196:199], v[124:127]
	v_mfma_f32_16x16x32_bf16 v[116:119], v[172:175], v[196:199], v[116:119]
	v_mfma_f32_16x16x32_bf16 v[108:111], v[144:147], v[204:207], v[108:111]
	v_mfma_f32_16x16x32_bf16 v[100:103], v[172:175], v[204:207], v[100:103]
	v_mfma_f32_16x16x32_bf16 v[92:95], v[144:147], v[214:217], v[92:95]
	v_mfma_f32_16x16x32_bf16 v[84:87], v[172:175], v[214:217], v[84:87]
	v_mfma_f32_16x16x32_bf16 v[76:79], v[144:147], v[222:225], v[76:79]
	v_mfma_f32_16x16x32_bf16 v[68:71], v[172:175], v[222:225], v[68:71]
	v_mfma_f32_16x16x32_bf16 v[124:127], v[168:171], v[200:203], v[124:127]
	v_mfma_f32_16x16x32_bf16 v[116:119], v[176:179], v[200:203], v[116:119]
	v_mfma_f32_16x16x32_bf16 v[108:111], v[168:171], v[210:213], v[108:111]
	v_mfma_f32_16x16x32_bf16 v[100:103], v[176:179], v[210:213], v[100:103]
	v_mfma_f32_16x16x32_bf16 v[92:95], v[168:171], v[218:221], v[92:95]
	v_mfma_f32_16x16x32_bf16 v[84:87], v[176:179], v[218:221], v[84:87]
	v_mfma_f32_16x16x32_bf16 v[76:79], v[168:171], v[226:229], v[76:79]
	v_mfma_f32_16x16x32_bf16 v[68:71], v[176:179], v[226:229], v[68:71]
	s_setprio 0
	s_setprio 1
	v_mfma_f32_16x16x32_bf16 v[120:123], v[180:183], v[196:199], v[120:123]
	v_mfma_f32_16x16x32_bf16 v[112:115], v[188:191], v[196:199], v[112:115]
	v_mfma_f32_16x16x32_bf16 v[104:107], v[180:183], v[204:207], v[104:107]
	v_mfma_f32_16x16x32_bf16 v[96:99], v[188:191], v[204:207], v[96:99]
	v_mfma_f32_16x16x32_bf16 v[88:91], v[180:183], v[214:217], v[88:91]
	v_mfma_f32_16x16x32_bf16 v[80:83], v[188:191], v[214:217], v[80:83]
	v_mfma_f32_16x16x32_bf16 v[72:75], v[180:183], v[222:225], v[72:75]
	v_mfma_f32_16x16x32_bf16 v[64:67], v[188:191], v[222:225], v[64:67]
	v_mfma_f32_16x16x32_bf16 v[120:123], v[184:187], v[200:203], v[120:123]
	v_mfma_f32_16x16x32_bf16 v[112:115], v[192:195], v[200:203], v[112:115]
	v_mfma_f32_16x16x32_bf16 v[104:107], v[184:187], v[210:213], v[104:107]
	v_mfma_f32_16x16x32_bf16 v[96:99], v[192:195], v[210:213], v[96:99]
	v_mfma_f32_16x16x32_bf16 v[88:91], v[184:187], v[218:221], v[88:91]
	v_mfma_f32_16x16x32_bf16 v[80:83], v[192:195], v[218:221], v[80:83]
	v_mfma_f32_16x16x32_bf16 v[72:75], v[184:187], v[226:229], v[72:75]
	s_barrier
; #define PG8_STAGE(bufoff, gbase, voff) do { _Pragma("unroll") for (int _i = 0; _i < 2; ++_i) \
;         __builtin_amdgcn_global_load_lds((const unsigned*)((const char*)(gbase) + (voff)[_i]), (PG8_LAS unsigned*)(lds + (bufoff) + ldsw + _i * 8192), 16, 0, 0); } while (0)
; #define PG8_LDA(dst, b, h) do { _Pragma("unroll") for (int m = 0; m < 4; ++m) _Pragma("unroll") for (int k = 0; k < 2; ++k) dst[m][k] = *(const PG8_LAS bf16x8*)(lds + PG8_SA(b, h) + aoff + m * 2048 + k * 1024); } while (0)
; #define PG8_MMA(ai, bj, At, Bt) do { __builtin_amdgcn_s_setprio(1); _Pragma("unroll") for (int m = 0; m < 4; ++m) _Pragma("unroll") for (int n = 0; n < 2; ++n) _Pragma("unroll") for (int k = 0; k < 2; ++k) \
;         acc[ai][bj][m][n] = __builtin_amdgcn_mfma_f32_16x16x32_bf16(Bt[n][k], At[m][k], acc[ai][bj][m][n], 0, 0, 0); __builtin_amdgcn_s_setprio(0); } while (0)
; #define PG8_WAIT_V(n) asm volatile("s_waitcnt vmcnt(" #n ")" ::: "memory")
; #define PG8_WAIT_L(n) asm volatile("s_waitcnt lgkmcnt(" #n ")" ::: "memory")
; #define PG8_BAR __builtin_amdgcn_s_barrier()
; #define PG8_SCHED __builtin_amdgcn_sched_barrier(0)
; template <class Epi, class Sched, bool ALIGN_EPI = false, bool SP2 = false>
; __device__ __forceinline__ void gemm_phase(PG8_LAS unsigned char* lds, const Gemm g, const Sched& S, const Epi& E) {
;     ...
;         for (int t = 0; t < nt; t += 2) {
;     ...
;             PG8_WAIT_V(8); PG8_WAIT_L(0); PG8_BAR; PG8_MMA(0, 0, At, B0); PG8_MMA(0, 1, At, B1); PG8_BAR; PG8_SCHED;
;             PG8_LDA(At, 1, 1); PG8_STAGE(PG8_SB(1, 0), b3, voffB); PG8_STAGE(PG8_SB(1, 1), b3 + hstep, voffB); PG8_STAGE(PG8_SA(1, 0), a3, voffA);
;             PG8_WAIT_V(8); PG8_WAIT_L(0); PG8_BAR; PG8_MMA(1, 0, At, B0); PG8_MMA(1, 1, At, B1); PG8_BAR; PG8_SCHED;
	v_mfma_f32_16x16x32_bf16 v[64:67], v[192:195], v[226:229], v[64:67]
	s_setprio 0
	s_add_i32 s42, s52, s64
	v_lshl_add_u64 v[148:149], v[148:149], 0, s[16:17]
	s_mov_b32 m0, s42
	ds_read_b128 v[196:199], v165 offset:49152
	ds_read_b128 v[200:203], v165 offset:50176
	ds_read_b128 v[204:207], v165 offset:51200
	ds_read_b128 v[210:213], v165 offset:52224
	ds_read_b128 v[214:217], v165 offset:53248
	ds_read_b128 v[218:221], v165 offset:54272
	ds_read_b128 v[222:225], v165 offset:55296
	ds_read_b128 v[226:229], v165 offset:56320
	global_load_lds_dwordx4 v[148:149], off
	s_add_i32 m0, s42, 0x2000
	s_add_u32 s40, s40, 0x40080
	v_lshl_add_u64 v[148:149], v[230:231], 0, s[16:17]
	s_addc_u32 s41, s41, 0
	s_add_i32 s42, s53, s64
	global_load_lds_dwordx4 v[148:149], off
	v_lshl_add_u64 v[148:149], s[40:41], 0, v[130:131]
	s_mov_b32 m0, s42
	s_nop 0
	global_load_lds_dwordx4 v[148:149], off
	v_lshl_add_u64 v[148:149], s[40:41], 0, v[134:135]
	s_add_i32 m0, s42, 0x2000
	s_nop 0
	global_load_lds_dwordx4 v[148:149], off
	v_lshl_add_u64 v[148:149], v[232:233], 0, s[16:17]
	s_mov_b32 m0, s74
	s_nop 0
	global_load_lds_dwordx4 v[148:149], off
	v_lshl_add_u64 v[148:149], v[234:235], 0, s[16:17]
	s_mov_b32 m0, s75
	s_nop 0
	global_load_lds_dwordx4 v[148:149], off
	s_waitcnt vmcnt(8)
	s_waitcnt lgkmcnt(0)
	s_barrier
	s_setprio 1
	s_waitcnt lgkmcnt(0)
	v_mfma_f32_16x16x32_bf16 v[60:63], v[144:147], v[196:199], v[60:63]
	v_mfma_f32_16x16x32_bf16 v[52:55], v[172:175], v[196:199], v[52:55]
	v_mfma_f32_16x16x32_bf16 v[44:47], v[144:147], v[204:207], v[44:47]
	v_mfma_f32_16x16x32_bf16 v[36:39], v[172:175], v[204:207], v[36:39]
	v_mfma_f32_16x16x32_bf16 v[28:31], v[144:147], v[214:217], v[28:31]
	v_mfma_f32_16x16x32_bf16 v[20:23], v[172:175], v[214:217], v[20:23]
	v_mfma_f32_16x16x32_bf16 v[12:15], v[144:147], v[222:225], v[12:15]
	v_mfma_f32_16x16x32_bf16 v[4:7], v[172:175], v[222:225], v[4:7]
	v_mfma_f32_16x16x32_bf16 v[60:63], v[168:171], v[200:203], v[60:63]
	v_mfma_f32_16x16x32_bf16 v[52:55], v[176:179], v[200:203], v[52:55]
	v_mfma_f32_16x16x32_bf16 v[44:47], v[168:171], v[210:213], v[44:47]
	v_mfma_f32_16x16x32_bf16 v[36:39], v[176:179], v[210:213], v[36:39]
	v_mfma_f32_16x16x32_bf16 v[28:31], v[168:171], v[218:221], v[28:31]
	v_mfma_f32_16x16x32_bf16 v[20:23], v[176:179], v[218:221], v[20:23]
	v_mfma_f32_16x16x32_bf16 v[12:15], v[168:171], v[226:229], v[12:15]
	v_mfma_f32_16x16x32_bf16 v[4:7], v[176:179], v[226:229], v[4:7]
	s_setprio 0
	s_setprio 1
	v_mfma_f32_16x16x32_bf16 v[56:59], v[180:183], v[196:199], v[56:59]
	v_mfma_f32_16x16x32_bf16 v[48:51], v[188:191], v[196:199], v[48:51]
	v_mfma_f32_16x16x32_bf16 v[40:43], v[180:183], v[204:207], v[40:43]
	v_mfma_f32_16x16x32_bf16 v[32:35], v[188:191], v[204:207], v[32:35]
	v_mfma_f32_16x16x32_bf16 v[24:27], v[180:183], v[214:217], v[24:27]
	v_mfma_f32_16x16x32_bf16 v[16:19], v[188:191], v[214:217], v[16:19]
	v_mfma_f32_16x16x32_bf16 v[8:11], v[180:183], v[222:225], v[8:11]
	v_mfma_f32_16x16x32_bf16 v[0:3], v[188:191], v[222:225], v[0:3]
	v_mfma_f32_16x16x32_bf16 v[56:59], v[184:187], v[200:203], v[56:59]
	v_mfma_f32_16x16x32_bf16 v[48:51], v[192:195], v[200:203], v[48:51]
	v_mfma_f32_16x16x32_bf16 v[40:43], v[184:187], v[210:213], v[40:43]
	v_mfma_f32_16x16x32_bf16 v[32:35], v[192:195], v[210:213], v[32:35]
	v_mfma_f32_16x16x32_bf16 v[24:27], v[184:187], v[218:221], v[24:27]
	v_mfma_f32_16x16x32_bf16 v[16:19], v[192:195], v[218:221], v[16:19]
	v_mfma_f32_16x16x32_bf16 v[8:11], v[184:187], v[226:229], v[8:11]
	s_barrier
	v_mfma_f32_16x16x32_bf16 v[0:3], v[192:195], v[226:229], v[0:3]
	s_setprio 0
	s_add_i32 s85, s85, 2
	s_add_u32 s38, s38, 0x100
	s_addc_u32 s39, s39, 0
	s_add_u32 s83, s83, 0x100
	s_addc_u32 s84, s84, 0
	s_cmp_gt_u32 s85, 13

; #define PG8_STAGE(bufoff, gbase, voff) do { _Pragma("unroll") for (int _i = 0; _i < 2; ++_i) \
;         __builtin_amdgcn_global_load_lds((const unsigned*)((const char*)(gbase) + (voff)[_i]), (PG8_LAS unsigned*)(lds + (bufoff) + ldsw + _i * 8192), 16, 0, 0); } while (0)
; #define PG8_LDA(dst, b, h) do { _Pragma("unroll") for (int m = 0; m < 4; ++m) _Pragma("unroll") for (int k = 0; k < 2; ++k) dst[m][k] = *(const PG8_LAS bf16x8*)(lds + PG8_SA(b, h) + aoff + m * 2048 + k * 1024); } while (0)
; #define PG8_LDB(dst, b, h) do { _Pragma("unroll") for (int n = 0; n < 2; ++n) _Pragma("unroll") for (int k = 0; k < 2; ++k) dst[n][k] = *(const PG8_LAS bf16x8*)(lds + PG8_SB(b, h) + boff + n * 2048 + k * 1024); } while (0)
; #define PG8_WAIT_V(n) asm volatile("s_waitcnt vmcnt(" #n ")" ::: "memory")
; #define PG8_WAIT_L(n) asm volatile("s_waitcnt lgkmcnt(" #n ")" ::: "memory")
; #define PG8_BAR __builtin_amdgcn_s_barrier()
; #define PG8_SCHED __builtin_amdgcn_sched_barrier(0)
; template <class Epi, class Sched, bool ALIGN_EPI = false, bool SP2 = false>
; __device__ __forceinline__ void gemm_phase(PG8_LAS unsigned char* lds, const Gemm g, const Sched& S, const Epi& E) {
;     ...
;         const bool has_next = S.next(ui + 1, nxt);
;         const char* nA = has_next ? (const char*)g.A + (size_t)nxt.pm * tstep : cA; const char* nB = has_next ? (const char*)g.Bt + (size_t)nxt.pn * tstep : cB;
;         for (int t = 0; t < nt; t += 2) {
;             const bool last = (t == nt - 2);
;             const char* a1 = cA + (size_t)(t + 1) * kstep;
;             const char* a2 = last ? nA : cA + (size_t)(t + 2) * kstep; const char* b2 = last ? nB : cB + (size_t)(t + 2) * kstep;
;             const char* a3 = a2 + kstep; const char* b3 = b2 + kstep;
;             if (last && has_next) S.a_ready(nxt);
;             if constexpr (SP2) {
;             PG8_LDB(B0, 0, 0); PG8_LDB(B1, 0, 1); PG8_SCHED; PG8_LDA(At, 0, 0); PG8_STAGE(PG8_SA(1, 1), a1 + hstep, voffA);
;             PG8_WAIT_V(8); PG8_WAIT_L(0); PG8_BAR; PG8_MMA(0, 0, At, B0); PG8_MMA(0, 1, At, B1); PG8_BAR; PG8_SCHED;
;             PG8_LDA(At, 0, 1); PG8_STAGE(PG8_SB(0, 0), b2, voffB); PG8_STAGE(PG8_SB(0, 1), b2 + hstep, voffB); PG8_STAGE(PG8_SA(0, 0), a2, voffA);
;             PG8_WAIT_V(8); PG8_WAIT_L(0); PG8_BAR; PG8_MMA(1, 0, At, B0); PG8_MMA(1, 1, At, B1); PG8_BAR; PG8_SCHED;
.LBB0_461:
	s_ashr_i32 s67, s66, 31
	s_lshl_b64 s[52:53], s[66:67], 19
	s_add_u32 s68, s54, s52
	s_addc_u32 s69, s55, s53
	s_and_b64 s[52:53], s[4:5], exec
	s_cselect_b32 s7, s69, s9
	s_cselect_b32 s67, s68, s8
	s_ashr_i32 s65, s64, 31
	s_lshl_b64 s[52:53], s[64:65], 19
	s_add_u32 s70, s25, s52
	s_addc_u32 s71, s59, s53
	s_and_b64 s[52:53], s[4:5], exec
	s_cselect_b32 s65, s71, s73
	s_cselect_b32 s95, s70, s72
	s_add_u32 s8, s8, 0x40080
	s_addc_u32 s9, s9, 0
	s_add_u32 s96, s72, 0x100
	v_mov_b32_e32 v0, 0
	s_addc_u32 s97, s73, 0
	s_mov_b32 vcc_lo, -2
	v_mov_b32_e32 v1, v0
	ds_read_b128 v[148:151], v167
	ds_read_b128 v[152:155], v167 offset:1024
	ds_read_b128 v[156:159], v167 offset:2048
	ds_read_b128 v[160:163], v167 offset:3072
	ds_read_b128 v[172:175], v168
	ds_read_b128 v[176:179], v168 offset:1024
	ds_read_b128 v[180:183], v168 offset:2048
	ds_read_b128 v[184:187], v168 offset:3072
	s_add_u32 s52, s8, 0xfffc0080
	s_addc_u32 s53, s9, -1
	s_cmp_eq_u32 vcc_lo, 12
	s_cselect_b32 s75, s7, s53
	s_cselect_b32 s74, s67, s52
	s_cselect_b32 s73, s65, s97
	s_cselect_b32 s72, s95, s96
	v_lshl_add_u64 v[164:165], s[8:9], 0, v[140:141]
	s_add_i32 m0, s76, 0xc000
	ds_read_b128 v[188:191], v169
	ds_read_b128 v[192:195], v169 offset:1024
	ds_read_b128 v[196:199], v169 offset:2048
	ds_read_b128 v[200:203], v169 offset:3072
	ds_read_b128 v[204:207], v169 offset:4096
	ds_read_b128 v[210:213], v169 offset:5120
	ds_read_b128 v[214:217], v169 offset:6144
	ds_read_b128 v[218:221], v169 offset:7168
	global_load_lds_dwordx4 v[164:165], off
	v_lshl_add_u64 v[164:165], s[8:9], 0, v[142:143]
	s_add_i32 m0, s76, 0xe000
	s_nop 0
	global_load_lds_dwordx4 v[164:165], off
	s_waitcnt vmcnt(8)
	s_waitcnt lgkmcnt(0)
	s_barrier
	s_setprio 1
	s_waitcnt lgkmcnt(0)
	v_mfma_f32_16x16x32_bf16 v[124:127], v[148:151], v[188:191], 0
	v_mfma_f32_16x16x32_bf16 v[120:123], v[156:159], v[188:191], 0
	v_mfma_f32_16x16x32_bf16 v[108:111], v[148:151], v[196:199], 0
	v_mfma_f32_16x16x32_bf16 v[104:107], v[156:159], v[196:199], 0
	v_mfma_f32_16x16x32_bf16 v[92:95], v[148:151], v[204:207], 0
	v_mfma_f32_16x16x32_bf16 v[88:91], v[156:159], v[204:207], 0
	v_mfma_f32_16x16x32_bf16 v[76:79], v[148:151], v[214:217], 0
	v_mfma_f32_16x16x32_bf16 v[72:75], v[156:159], v[214:217], 0
	v_mfma_f32_16x16x32_bf16 v[124:127], v[152:155], v[192:195], v[124:127]
	v_mfma_f32_16x16x32_bf16 v[120:123], v[160:163], v[192:195], v[120:123]
	v_mfma_f32_16x16x32_bf16 v[108:111], v[152:155], v[200:203], v[108:111]
	v_mfma_f32_16x16x32_bf16 v[104:107], v[160:163], v[200:203], v[104:107]
	v_mfma_f32_16x16x32_bf16 v[92:95], v[152:155], v[210:213], v[92:95]
	v_mfma_f32_16x16x32_bf16 v[88:91], v[160:163], v[210:213], v[88:91]
	v_mfma_f32_16x16x32_bf16 v[76:79], v[152:155], v[218:221], v[76:79]
	v_mfma_f32_16x16x32_bf16 v[72:75], v[160:163], v[218:221], v[72:75]
	s_setprio 0
	s_setprio 1
	v_mfma_f32_16x16x32_bf16 v[116:119], v[172:175], v[188:191], 0
	v_mfma_f32_16x16x32_bf16 v[112:115], v[180:183], v[188:191], 0
	v_mfma_f32_16x16x32_bf16 v[100:103], v[172:175], v[196:199], 0
	v_mfma_f32_16x16x32_bf16 v[96:99], v[180:183], v[196:199], 0
	v_mfma_f32_16x16x32_bf16 v[84:87], v[172:175], v[204:207], 0
	v_mfma_f32_16x16x32_bf16 v[80:83], v[180:183], v[204:207], 0
	v_mfma_f32_16x16x32_bf16 v[68:71], v[172:175], v[214:217], 0
	v_mfma_f32_16x16x32_bf16 v[64:67], v[180:183], v[214:217], 0
	v_mfma_f32_16x16x32_bf16 v[116:119], v[176:179], v[192:195], v[116:119]
	v_mfma_f32_16x16x32_bf16 v[112:115], v[184:187], v[192:195], v[112:115]
	v_mfma_f32_16x16x32_bf16 v[100:103], v[176:179], v[200:203], v[100:103]
	v_mfma_f32_16x16x32_bf16 v[96:99], v[184:187], v[200:203], v[96:99]
	v_mfma_f32_16x16x32_bf16 v[84:87], v[176:179], v[210:213], v[84:87]
	v_mfma_f32_16x16x32_bf16 v[80:83], v[184:187], v[210:213], v[80:83]
	v_mfma_f32_16x16x32_bf16 v[68:71], v[176:179], v[218:221], v[68:71]
	s_barrier
	v_mfma_f32_16x16x32_bf16 v[64:67], v[184:187], v[218:221], v[64:67]
	s_setprio 0
	s_add_i32 s52, s85, s61
	v_lshl_add_u64 v[164:165], s[72:73], 0, v[130:131]
	s_mov_b32 m0, s52
	ds_read_b128 v[188:191], v169 offset:16384
	ds_read_b128 v[192:195], v169 offset:17408
	ds_read_b128 v[196:199], v169 offset:18432
	ds_read_b128 v[200:203], v169 offset:19456
	ds_read_b128 v[204:207], v169 offset:20480
	ds_read_b128 v[210:213], v169 offset:21504
	ds_read_b128 v[214:217], v169 offset:22528
	ds_read_b128 v[218:221], v169 offset:23552
	global_load_lds_dwordx4 v[164:165], off
	s_add_i32 m0, s52, 0x2000
	s_add_u32 s52, s72, 0x40000
	v_lshl_add_u64 v[222:223], s[72:73], 0, v[134:135]
	s_addc_u32 s53, s73, 0
	s_add_i32 s78, s86, s61
	global_load_lds_dwordx4 v[222:223], off
	v_lshl_add_u64 v[224:225], s[52:53], 0, v[130:131]
	s_mov_b32 m0, s78
	v_lshl_add_u64 v[226:227], s[74:75], 0, v[132:133]
	global_load_lds_dwordx4 v[224:225], off
	v_lshl_add_u64 v[224:225], s[52:53], 0, v[134:135]
	s_add_i32 m0, s78, 0x2000
	s_nop 0
	global_load_lds_dwordx4 v[224:225], off
	v_lshl_add_u64 v[224:225], s[74:75], 0, v[128:129]
	s_mov_b32 m0, s76
	s_nop 0
	global_load_lds_dwordx4 v[224:225], off
	s_mov_b32 m0, s77
	s_nop 0
	global_load_lds_dwordx4 v[226:227], off
	s_waitcnt vmcnt(8)
	s_waitcnt lgkmcnt(0)
	s_barrier
; #define PG8_STAGE(bufoff, gbase, voff) do { _Pragma("unroll") for (int _i = 0; _i < 2; ++_i) \
;         __builtin_amdgcn_global_load_lds((const unsigned*)((const char*)(gbase) + (voff)[_i]), (PG8_LAS unsigned*)(lds + (bufoff) + ldsw + _i * 8192), 16, 0, 0); } while (0)
; #define PG8_LDA(dst, b, h) do { _Pragma("unroll") for (int m = 0; m < 4; ++m) _Pragma("unroll") for (int k = 0; k < 2; ++k) dst[m][k] = *(const PG8_LAS bf16x8*)(lds + PG8_SA(b, h) + aoff + m * 2048 + k * 1024); } while (0)
; #define PG8_LDB(dst, b, h) do { _Pragma("unroll") for (int n = 0; n < 2; ++n) _Pragma("unroll") for (int k = 0; k < 2; ++k) dst[n][k] = *(const PG8_LAS bf16x8*)(lds + PG8_SB(b, h) + boff + n * 2048 + k * 1024); } while (0)
; #define PG8_MMA(ai, bj, At, Bt) do { __builtin_amdgcn_s_setprio(1); _Pragma("unroll") for (int m = 0; m < 4; ++m) _Pragma("unroll") for (int n = 0; n < 2; ++n) _Pragma("unroll") for (int k = 0; k < 2; ++k) \
;         acc[ai][bj][m][n] = __builtin_amdgcn_mfma_f32_16x16x32_bf16(Bt[n][k], At[m][k], acc[ai][bj][m][n], 0, 0, 0); __builtin_amdgcn_s_setprio(0); } while (0)
; #define PG8_WAIT_V(n) asm volatile("s_waitcnt vmcnt(" #n ")" ::: "memory")
; #define PG8_WAIT_L(n) asm volatile("s_waitcnt lgkmcnt(" #n ")" ::: "memory")
; #define PG8_BAR __builtin_amdgcn_s_barrier()
; #define PG8_SCHED __builtin_amdgcn_sched_barrier(0)
; template <class Epi, class Sched, bool ALIGN_EPI = false, bool SP2 = false>
; __device__ __forceinline__ void gemm_phase(PG8_LAS unsigned char* lds, const Gemm g, const Sched& S, const Epi& E) {
;     ...
;             PG8_WAIT_V(8); PG8_WAIT_L(0); PG8_BAR; PG8_MMA(0, 0, At, B0); PG8_MMA(0, 1, At, B1); PG8_BAR; PG8_SCHED;
;             PG8_LDA(At, 0, 1); PG8_STAGE(PG8_SB(0, 0), b2, voffB); PG8_STAGE(PG8_SB(0, 1), b2 + hstep, voffB); PG8_STAGE(PG8_SA(0, 0), a2, voffA);
;             PG8_WAIT_V(8); PG8_WAIT_L(0); PG8_BAR; PG8_MMA(1, 0, At, B0); PG8_MMA(1, 1, At, B1); PG8_BAR; PG8_SCHED;
;             PG8_LDB(B0, 1, 0); PG8_LDB(B1, 1, 1); PG8_SCHED; PG8_LDA(At, 1, 0); PG8_STAGE(PG8_SA(0, 1), a2 + hstep, voffA);
;             PG8_WAIT_V(8); PG8_WAIT_L(0); PG8_BAR; PG8_MMA(0, 0, At, B0); PG8_MMA(0, 1, At, B1); PG8_BAR; PG8_SCHED;
	s_setprio 1
	s_waitcnt lgkmcnt(0)
	v_mfma_f32_16x16x32_bf16 v[60:63], v[148:151], v[188:191], 0
	v_mfma_f32_16x16x32_bf16 v[56:59], v[156:159], v[188:191], 0
	v_mfma_f32_16x16x32_bf16 v[44:47], v[148:151], v[196:199], 0
	v_mfma_f32_16x16x32_bf16 v[40:43], v[156:159], v[196:199], 0
	v_mfma_f32_16x16x32_bf16 v[28:31], v[148:151], v[204:207], 0
	v_mfma_f32_16x16x32_bf16 v[24:27], v[156:159], v[204:207], 0
	v_mfma_f32_16x16x32_bf16 v[12:15], v[148:151], v[214:217], 0
	v_mfma_f32_16x16x32_bf16 v[8:11], v[156:159], v[214:217], 0
	v_mfma_f32_16x16x32_bf16 v[60:63], v[152:155], v[192:195], v[60:63]
	v_mfma_f32_16x16x32_bf16 v[56:59], v[160:163], v[192:195], v[56:59]
	v_mfma_f32_16x16x32_bf16 v[44:47], v[152:155], v[200:203], v[44:47]
	v_mfma_f32_16x16x32_bf16 v[40:43], v[160:163], v[200:203], v[40:43]
	v_mfma_f32_16x16x32_bf16 v[28:31], v[152:155], v[210:213], v[28:31]
	v_mfma_f32_16x16x32_bf16 v[24:27], v[160:163], v[210:213], v[24:27]
	v_mfma_f32_16x16x32_bf16 v[12:15], v[152:155], v[218:221], v[12:15]
	v_mfma_f32_16x16x32_bf16 v[8:11], v[160:163], v[218:221], v[8:11]
	s_setprio 0
	s_setprio 1
	v_mfma_f32_16x16x32_bf16 v[52:55], v[172:175], v[188:191], 0
	v_mfma_f32_16x16x32_bf16 v[48:51], v[180:183], v[188:191], 0
	v_mfma_f32_16x16x32_bf16 v[36:39], v[172:175], v[196:199], 0
	v_mfma_f32_16x16x32_bf16 v[32:35], v[180:183], v[196:199], 0
	v_mfma_f32_16x16x32_bf16 v[20:23], v[172:175], v[204:207], 0
	v_mfma_f32_16x16x32_bf16 v[16:19], v[180:183], v[204:207], 0
	v_mfma_f32_16x16x32_bf16 v[4:7], v[172:175], v[214:217], 0
	v_mfma_f32_16x16x32_bf16 v[0:3], v[180:183], v[214:217], 0
	v_mfma_f32_16x16x32_bf16 v[52:55], v[176:179], v[192:195], v[52:55]
	v_mfma_f32_16x16x32_bf16 v[48:51], v[184:187], v[192:195], v[48:51]
	v_mfma_f32_16x16x32_bf16 v[36:39], v[176:179], v[200:203], v[36:39]
	v_mfma_f32_16x16x32_bf16 v[32:35], v[184:187], v[200:203], v[32:35]
	v_mfma_f32_16x16x32_bf16 v[20:23], v[176:179], v[210:213], v[20:23]
	v_mfma_f32_16x16x32_bf16 v[16:19], v[184:187], v[210:213], v[16:19]
	v_mfma_f32_16x16x32_bf16 v[4:7], v[176:179], v[218:221], v[4:7]
	s_barrier
	v_mfma_f32_16x16x32_bf16 v[0:3], v[184:187], v[218:221], v[0:3]
	s_setprio 0
	s_add_i32 s78, 0, 0x18000
	v_add_u32_e32 v136, s78, v166
	s_add_i32 vcc_hi, 0, 0x1c000
	ds_read_b128 v[148:151], v136
	ds_read_b128 v[152:155], v136 offset:1024
	ds_read_b128 v[156:159], v136 offset:2048
	ds_read_b128 v[160:163], v136 offset:3072
	v_add_u32_e32 v136, vcc_hi, v166
	ds_read_b128 v[172:175], v136
	ds_read_b128 v[176:179], v136 offset:1024
	ds_read_b128 v[180:183], v136 offset:2048
	ds_read_b128 v[184:187], v136 offset:3072
	s_add_u32 s52, s74, 0x40000
	s_addc_u32 s53, s75, 0
	s_mov_b32 m0, s79
	v_lshl_add_u64 v[228:229], s[52:53], 0, v[128:129]
	ds_read_b128 v[188:191], v169 offset:32768
	ds_read_b128 v[192:195], v169 offset:33792
	ds_read_b128 v[196:199], v169 offset:34816
	ds_read_b128 v[200:203], v169 offset:35840
	ds_read_b128 v[204:207], v169 offset:36864
	ds_read_b128 v[210:213], v169 offset:37888
	ds_read_b128 v[214:217], v169 offset:38912
	ds_read_b128 v[218:221], v169 offset:39936
	global_load_lds_dwordx4 v[228:229], off
	v_lshl_add_u64 v[228:229], s[52:53], 0, v[132:133]
	s_mov_b32 m0, s80
	s_nop 0
	global_load_lds_dwordx4 v[228:229], off
	s_waitcnt vmcnt(8)
	s_waitcnt lgkmcnt(0)
	s_barrier
	s_setprio 1
	s_waitcnt lgkmcnt(0)
	v_mfma_f32_16x16x32_bf16 v[124:127], v[148:151], v[188:191], v[124:127]
	v_mfma_f32_16x16x32_bf16 v[120:123], v[156:159], v[188:191], v[120:123]
	v_mfma_f32_16x16x32_bf16 v[108:111], v[148:151], v[196:199], v[108:111]
	v_mfma_f32_16x16x32_bf16 v[104:107], v[156:159], v[196:199], v[104:107]
	v_mfma_f32_16x16x32_bf16 v[92:95], v[148:151], v[204:207], v[92:95]
	v_mfma_f32_16x16x32_bf16 v[88:91], v[156:159], v[204:207], v[88:91]
	v_mfma_f32_16x16x32_bf16 v[76:79], v[148:151], v[214:217], v[76:79]
	v_mfma_f32_16x16x32_bf16 v[72:75], v[156:159], v[214:217], v[72:75]
	v_mfma_f32_16x16x32_bf16 v[124:127], v[152:155], v[192:195], v[124:127]
	v_mfma_f32_16x16x32_bf16 v[120:123], v[160:163], v[192:195], v[120:123]
	v_mfma_f32_16x16x32_bf16 v[108:111], v[152:155], v[200:203], v[108:111]
	v_mfma_f32_16x16x32_bf16 v[104:107], v[160:163], v[200:203], v[104:107]
	v_mfma_f32_16x16x32_bf16 v[92:95], v[152:155], v[210:213], v[92:95]
	v_mfma_f32_16x16x32_bf16 v[88:91], v[160:163], v[210:213], v[88:91]
	v_mfma_f32_16x16x32_bf16 v[76:79], v[152:155], v[218:221], v[76:79]
	v_mfma_f32_16x16x32_bf16 v[72:75], v[160:163], v[218:221], v[72:75]
	s_setprio 0
	s_setprio 1
	v_mfma_f32_16x16x32_bf16 v[116:119], v[172:175], v[188:191], v[116:119]
	v_mfma_f32_16x16x32_bf16 v[112:115], v[180:183], v[188:191], v[112:115]
	v_mfma_f32_16x16x32_bf16 v[100:103], v[172:175], v[196:199], v[100:103]
	v_mfma_f32_16x16x32_bf16 v[96:99], v[180:183], v[196:199], v[96:99]
	v_mfma_f32_16x16x32_bf16 v[84:87], v[172:175], v[204:207], v[84:87]
	v_mfma_f32_16x16x32_bf16 v[80:83], v[180:183], v[204:207], v[80:83]
	v_mfma_f32_16x16x32_bf16 v[68:71], v[172:175], v[214:217], v[68:71]
	v_mfma_f32_16x16x32_bf16 v[64:67], v[180:183], v[214:217], v[64:67]
	v_mfma_f32_16x16x32_bf16 v[116:119], v[176:179], v[192:195], v[116:119]
	v_mfma_f32_16x16x32_bf16 v[112:115], v[184:187], v[192:195], v[112:115]
	v_mfma_f32_16x16x32_bf16 v[100:103], v[176:179], v[200:203], v[100:103]
	v_mfma_f32_16x16x32_bf16 v[96:99], v[184:187], v[200:203], v[96:99]
	v_mfma_f32_16x16x32_bf16 v[84:87], v[176:179], v[210:213], v[84:87]
	v_mfma_f32_16x16x32_bf16 v[80:83], v[184:187], v[210:213], v[80:83]
	v_mfma_f32_16x16x32_bf16 v[68:71], v[176:179], v[218:221], v[68:71]
	s_barrier
; #define PG8_STAGE(bufoff, gbase, voff) do { _Pragma("unroll") for (int _i = 0; _i < 2; ++_i) \
;         __builtin_amdgcn_global_load_lds((const unsigned*)((const char*)(gbase) + (voff)[_i]), (PG8_LAS unsigned*)(lds + (bufoff) + ldsw + _i * 8192), 16, 0, 0); } while (0)
; #define PG8_LDA(dst, b, h) do { _Pragma("unroll") for (int m = 0; m < 4; ++m) _Pragma("unroll") for (int k = 0; k < 2; ++k) dst[m][k] = *(const PG8_LAS bf16x8*)(lds + PG8_SA(b, h) + aoff + m * 2048 + k * 1024); } while (0)
; #define PG8_MMA(ai, bj, At, Bt) do { __builtin_amdgcn_s_setprio(1); _Pragma("unroll") for (int m = 0; m < 4; ++m) _Pragma("unroll") for (int n = 0; n < 2; ++n) _Pragma("unroll") for (int k = 0; k < 2; ++k) \
;         acc[ai][bj][m][n] = __builtin_amdgcn_mfma_f32_16x16x32_bf16(Bt[n][k], At[m][k], acc[ai][bj][m][n], 0, 0, 0); __builtin_amdgcn_s_setprio(0); } while (0)
; #define PG8_WAIT_V(n) asm volatile("s_waitcnt vmcnt(" #n ")" ::: "memory")
; #define PG8_WAIT_L(n) asm volatile("s_waitcnt lgkmcnt(" #n ")" ::: "memory")
; #define PG8_BAR __builtin_amdgcn_s_barrier()
; #define PG8_SCHED __builtin_amdgcn_sched_barrier(0)
; template <class Epi, class Sched, bool ALIGN_EPI = false, bool SP2 = false>
; __device__ __forceinline__ void gemm_phase(PG8_LAS unsigned char* lds, const Gemm g, const Sched& S, const Epi& E) {
;     ...
;         for (int t = 0; t < nt; t += 2) {
;     ...
;             PG8_WAIT_V(8); PG8_WAIT_L(0); PG8_BAR; PG8_MMA(0, 0, At, B0); PG8_MMA(0, 1, At, B1); PG8_BAR; PG8_SCHED;
;             PG8_LDA(At, 1, 1); PG8_STAGE(PG8_SB(1, 0), b3, voffB); PG8_STAGE(PG8_SB(1, 1), b3 + hstep, voffB); PG8_STAGE(PG8_SA(1, 0), a3, voffA);
;             PG8_WAIT_V(8); PG8_WAIT_L(0); PG8_BAR; PG8_MMA(1, 0, At, B0); PG8_MMA(1, 1, At, B1); PG8_BAR; PG8_SCHED;
	v_mfma_f32_16x16x32_bf16 v[64:67], v[184:187], v[218:221], v[64:67]
	s_setprio 0
	s_add_i32 s52, s78, s61
	v_lshl_add_u64 v[164:165], v[164:165], 0, s[34:35]
	s_mov_b32 m0, s52
	ds_read_b128 v[188:191], v169 offset:49152
	ds_read_b128 v[192:195], v169 offset:50176
	ds_read_b128 v[196:199], v169 offset:51200
	ds_read_b128 v[200:203], v169 offset:52224
	ds_read_b128 v[204:207], v169 offset:53248
	ds_read_b128 v[210:213], v169 offset:54272
	ds_read_b128 v[214:217], v169 offset:55296
	ds_read_b128 v[218:221], v169 offset:56320
	global_load_lds_dwordx4 v[164:165], off
	s_add_i32 m0, s52, 0x2000
	s_add_u32 s52, s72, 0x40080
	v_lshl_add_u64 v[164:165], v[222:223], 0, s[34:35]
	s_addc_u32 s53, s73, 0
	s_add_i32 s72, vcc_hi, s61
	global_load_lds_dwordx4 v[164:165], off
	v_lshl_add_u64 v[164:165], s[52:53], 0, v[130:131]
	s_mov_b32 m0, s72
	s_nop 0
	global_load_lds_dwordx4 v[164:165], off
	v_lshl_add_u64 v[164:165], s[52:53], 0, v[134:135]
	s_add_i32 m0, s72, 0x2000
	s_nop 0
	global_load_lds_dwordx4 v[164:165], off
	v_lshl_add_u64 v[164:165], v[224:225], 0, s[34:35]
	s_mov_b32 m0, s83
	s_nop 0
	global_load_lds_dwordx4 v[164:165], off
	v_lshl_add_u64 v[164:165], v[226:227], 0, s[34:35]
	s_mov_b32 m0, s84
	s_nop 0
	global_load_lds_dwordx4 v[164:165], off
	s_waitcnt vmcnt(8)
	s_waitcnt lgkmcnt(0)
	s_barrier
	s_setprio 1
	s_waitcnt lgkmcnt(0)
	v_mfma_f32_16x16x32_bf16 v[60:63], v[148:151], v[188:191], v[60:63]
	v_mfma_f32_16x16x32_bf16 v[56:59], v[156:159], v[188:191], v[56:59]
	v_mfma_f32_16x16x32_bf16 v[44:47], v[148:151], v[196:199], v[44:47]
	v_mfma_f32_16x16x32_bf16 v[40:43], v[156:159], v[196:199], v[40:43]
	v_mfma_f32_16x16x32_bf16 v[28:31], v[148:151], v[204:207], v[28:31]
	v_mfma_f32_16x16x32_bf16 v[24:27], v[156:159], v[204:207], v[24:27]
	v_mfma_f32_16x16x32_bf16 v[12:15], v[148:151], v[214:217], v[12:15]
	v_mfma_f32_16x16x32_bf16 v[8:11], v[156:159], v[214:217], v[8:11]
	v_mfma_f32_16x16x32_bf16 v[60:63], v[152:155], v[192:195], v[60:63]
	v_mfma_f32_16x16x32_bf16 v[56:59], v[160:163], v[192:195], v[56:59]
	v_mfma_f32_16x16x32_bf16 v[44:47], v[152:155], v[200:203], v[44:47]
	v_mfma_f32_16x16x32_bf16 v[40:43], v[160:163], v[200:203], v[40:43]
	v_mfma_f32_16x16x32_bf16 v[28:31], v[152:155], v[210:213], v[28:31]
	v_mfma_f32_16x16x32_bf16 v[24:27], v[160:163], v[210:213], v[24:27]
	v_mfma_f32_16x16x32_bf16 v[12:15], v[152:155], v[218:221], v[12:15]
	v_mfma_f32_16x16x32_bf16 v[8:11], v[160:163], v[218:221], v[8:11]
	s_setprio 0
	s_setprio 1
	v_mfma_f32_16x16x32_bf16 v[52:55], v[172:175], v[188:191], v[52:55]
	v_mfma_f32_16x16x32_bf16 v[48:51], v[180:183], v[188:191], v[48:51]
	v_mfma_f32_16x16x32_bf16 v[36:39], v[172:175], v[196:199], v[36:39]
	v_mfma_f32_16x16x32_bf16 v[32:35], v[180:183], v[196:199], v[32:35]
	v_mfma_f32_16x16x32_bf16 v[20:23], v[172:175], v[204:207], v[20:23]
	v_mfma_f32_16x16x32_bf16 v[16:19], v[180:183], v[204:207], v[16:19]
	v_mfma_f32_16x16x32_bf16 v[4:7], v[172:175], v[214:217], v[4:7]
	v_mfma_f32_16x16x32_bf16 v[0:3], v[180:183], v[214:217], v[0:3]
	v_mfma_f32_16x16x32_bf16 v[52:55], v[176:179], v[192:195], v[52:55]
	v_mfma_f32_16x16x32_bf16 v[48:51], v[184:187], v[192:195], v[48:51]
	v_mfma_f32_16x16x32_bf16 v[36:39], v[176:179], v[200:203], v[36:39]
	v_mfma_f32_16x16x32_bf16 v[32:35], v[184:187], v[200:203], v[32:35]
	v_mfma_f32_16x16x32_bf16 v[20:23], v[176:179], v[210:213], v[20:23]
	v_mfma_f32_16x16x32_bf16 v[16:19], v[184:187], v[210:213], v[16:19]
	v_mfma_f32_16x16x32_bf16 v[4:7], v[176:179], v[218:221], v[4:7]
	s_barrier
	v_mfma_f32_16x16x32_bf16 v[0:3], v[184:187], v[218:221], v[0:3]
	s_setprio 0
	s_add_i32 vcc_lo, vcc_lo, 2
	s_add_u32 s8, s8, 0x100
	s_addc_u32 s9, s9, 0
	s_add_u32 s96, s96, 0x100
	s_addc_u32 s97, s97, 0
	s_cmp_gt_u32 vcc_lo, 13

; #define PG8_STAGE(bufoff, gbase, voff) do { _Pragma("unroll") for (int _i = 0; _i < 2; ++_i) \
;         __builtin_amdgcn_global_load_lds((const unsigned*)((const char*)(gbase) + (voff)[_i]), (PG8_LAS unsigned*)(lds + (bufoff) + ldsw + _i * 8192), 16, 0, 0); } while (0)
; #define PG8_LDA(dst, b, h) do { _Pragma("unroll") for (int m = 0; m < 4; ++m) _Pragma("unroll") for (int k = 0; k < 2; ++k) dst[m][k] = *(const PG8_LAS bf16x8*)(lds + PG8_SA(b, h) + aoff + m * 2048 + k * 1024); } while (0)
; #define PG8_LDB(dst, b, h) do { _Pragma("unroll") for (int n = 0; n < 2; ++n) _Pragma("unroll") for (int k = 0; k < 2; ++k) dst[n][k] = *(const PG8_LAS bf16x8*)(lds + PG8_SB(b, h) + boff + n * 2048 + k * 1024); } while (0)
; #define PG8_WAIT_V(n) asm volatile("s_waitcnt vmcnt(" #n ")" ::: "memory")
; #define PG8_WAIT_L(n) asm volatile("s_waitcnt lgkmcnt(" #n ")" ::: "memory")
; #define PG8_BAR __builtin_amdgcn_s_barrier()
; #define PG8_SCHED __builtin_amdgcn_sched_barrier(0)
; template <class Epi, class Sched, bool ALIGN_EPI = false, bool SP2 = false>
; __device__ __forceinline__ void gemm_phase(PG8_LAS unsigned char* lds, const Gemm g, const Sched& S, const Epi& E) {
;     ...
;         const bool has_next = S.next(ui + 1, nxt);
;         const char* nA = has_next ? (const char*)g.A + (size_t)nxt.pm * tstep : cA; const char* nB = has_next ? (const char*)g.Bt + (size_t)nxt.pn * tstep : cB;
;         for (int t = 0; t < nt; t += 2) {
;             const bool last = (t == nt - 2);
;             const char* a1 = cA + (size_t)(t + 1) * kstep;
;             const char* a2 = last ? nA : cA + (size_t)(t + 2) * kstep; const char* b2 = last ? nB : cB + (size_t)(t + 2) * kstep;
;             const char* a3 = a2 + kstep; const char* b3 = b2 + kstep;
;             if (last && has_next) S.a_ready(nxt);
;             if constexpr (SP2) {
;             PG8_LDB(B0, 0, 0); PG8_LDB(B1, 0, 1); PG8_SCHED; PG8_LDA(At, 0, 0); PG8_STAGE(PG8_SA(1, 1), a1 + hstep, voffA);
;             PG8_WAIT_V(8); PG8_WAIT_L(0); PG8_BAR; PG8_MMA(0, 0, At, B0); PG8_MMA(0, 1, At, B1); PG8_BAR; PG8_SCHED;
;             PG8_LDA(At, 0, 1); PG8_STAGE(PG8_SB(0, 0), b2, voffB); PG8_STAGE(PG8_SB(0, 1), b2 + hstep, voffB); PG8_STAGE(PG8_SA(0, 0), a2, voffA);
;             PG8_WAIT_V(8); PG8_WAIT_L(0); PG8_BAR; PG8_MMA(1, 0, At, B0); PG8_MMA(1, 1, At, B1); PG8_BAR; PG8_SCHED;
.LBB0_595:
	s_ashr_i32 s67, s66, 31
	s_lshl_b64 s[52:53], s[66:67], 19
	s_add_u32 s68, s54, s52
	s_addc_u32 s69, s55, s53
	s_and_b64 s[52:53], s[4:5], exec
	s_cselect_b32 s7, s69, s73
	s_cselect_b32 s9, s68, s72
	s_ashr_i32 s65, s64, 31
	s_lshl_b64 s[52:53], s[64:65], 19
	s_add_u32 s70, s79, s52
	s_addc_u32 s71, s80, s53
	s_and_b64 s[52:53], s[4:5], exec
	s_cselect_b32 s18, s71, s75
	s_cselect_b32 s65, s70, s74
	s_add_u32 s72, s72, 0x40080
	s_addc_u32 s73, s73, 0
	s_add_u32 s67, s74, 0x100
	v_mov_b32_e32 v0, 0
	s_addc_u32 vcc_lo, s75, 0
	s_mov_b32 vcc_hi, -2
	v_mov_b32_e32 v1, v0
	ds_read_b128 v[148:151], v167
	ds_read_b128 v[152:155], v167 offset:1024
	ds_read_b128 v[156:159], v167 offset:2048
	ds_read_b128 v[160:163], v167 offset:3072
	ds_read_b128 v[172:175], v168
	ds_read_b128 v[176:179], v168 offset:1024
	ds_read_b128 v[180:183], v168 offset:2048
	ds_read_b128 v[184:187], v168 offset:3072
	s_add_u32 s52, s72, 0xfffc0080
	s_addc_u32 s53, s73, -1
	s_cmp_eq_u32 vcc_hi, 12
	s_cselect_b32 s77, s7, s53
	s_cselect_b32 s76, s9, s52
	s_cselect_b32 s75, s18, vcc_lo
	s_cselect_b32 s74, s65, s67
	v_lshl_add_u64 v[164:165], s[72:73], 0, v[140:141]
	s_add_i32 m0, s81, 0xc000
	ds_read_b128 v[188:191], v169
	ds_read_b128 v[192:195], v169 offset:1024
	ds_read_b128 v[196:199], v169 offset:2048
	ds_read_b128 v[200:203], v169 offset:3072
	ds_read_b128 v[204:207], v169 offset:4096
	ds_read_b128 v[210:213], v169 offset:5120
	ds_read_b128 v[214:217], v169 offset:6144
	ds_read_b128 v[218:221], v169 offset:7168
	global_load_lds_dwordx4 v[164:165], off
	v_lshl_add_u64 v[164:165], s[72:73], 0, v[142:143]
	s_add_i32 m0, s81, 0xe000
	s_nop 0
	global_load_lds_dwordx4 v[164:165], off
	s_waitcnt vmcnt(8)
	s_waitcnt lgkmcnt(0)
	s_barrier
	s_setprio 1
	s_waitcnt lgkmcnt(0)
	v_mfma_f32_16x16x32_bf16 v[124:127], v[148:151], v[188:191], 0
	v_mfma_f32_16x16x32_bf16 v[120:123], v[156:159], v[188:191], 0
	v_mfma_f32_16x16x32_bf16 v[108:111], v[148:151], v[196:199], 0
	v_mfma_f32_16x16x32_bf16 v[104:107], v[156:159], v[196:199], 0
	v_mfma_f32_16x16x32_bf16 v[92:95], v[148:151], v[204:207], 0
	v_mfma_f32_16x16x32_bf16 v[88:91], v[156:159], v[204:207], 0
	v_mfma_f32_16x16x32_bf16 v[76:79], v[148:151], v[214:217], 0
	v_mfma_f32_16x16x32_bf16 v[72:75], v[156:159], v[214:217], 0
	v_mfma_f32_16x16x32_bf16 v[124:127], v[152:155], v[192:195], v[124:127]
	v_mfma_f32_16x16x32_bf16 v[120:123], v[160:163], v[192:195], v[120:123]
	v_mfma_f32_16x16x32_bf16 v[108:111], v[152:155], v[200:203], v[108:111]
	v_mfma_f32_16x16x32_bf16 v[104:107], v[160:163], v[200:203], v[104:107]
	v_mfma_f32_16x16x32_bf16 v[92:95], v[152:155], v[210:213], v[92:95]
	v_mfma_f32_16x16x32_bf16 v[88:91], v[160:163], v[210:213], v[88:91]
	v_mfma_f32_16x16x32_bf16 v[76:79], v[152:155], v[218:221], v[76:79]
	v_mfma_f32_16x16x32_bf16 v[72:75], v[160:163], v[218:221], v[72:75]
	s_setprio 0
	s_setprio 1
	v_mfma_f32_16x16x32_bf16 v[116:119], v[172:175], v[188:191], 0
	v_mfma_f32_16x16x32_bf16 v[112:115], v[180:183], v[188:191], 0
	v_mfma_f32_16x16x32_bf16 v[100:103], v[172:175], v[196:199], 0
	v_mfma_f32_16x16x32_bf16 v[96:99], v[180:183], v[196:199], 0
	v_mfma_f32_16x16x32_bf16 v[84:87], v[172:175], v[204:207], 0
	v_mfma_f32_16x16x32_bf16 v[80:83], v[180:183], v[204:207], 0
	v_mfma_f32_16x16x32_bf16 v[68:71], v[172:175], v[214:217], 0
	v_mfma_f32_16x16x32_bf16 v[64:67], v[180:183], v[214:217], 0
	v_mfma_f32_16x16x32_bf16 v[116:119], v[176:179], v[192:195], v[116:119]
	v_mfma_f32_16x16x32_bf16 v[112:115], v[184:187], v[192:195], v[112:115]
	v_mfma_f32_16x16x32_bf16 v[100:103], v[176:179], v[200:203], v[100:103]
	v_mfma_f32_16x16x32_bf16 v[96:99], v[184:187], v[200:203], v[96:99]
	v_mfma_f32_16x16x32_bf16 v[84:87], v[176:179], v[210:213], v[84:87]
	v_mfma_f32_16x16x32_bf16 v[80:83], v[184:187], v[210:213], v[80:83]
	v_mfma_f32_16x16x32_bf16 v[68:71], v[176:179], v[218:221], v[68:71]
	s_barrier
	v_mfma_f32_16x16x32_bf16 v[64:67], v[184:187], v[218:221], v[64:67]
	s_setprio 0
	s_add_i32 s52, s88, s61
	v_lshl_add_u64 v[164:165], s[74:75], 0, v[130:131]
	s_mov_b32 m0, s52
	ds_read_b128 v[188:191], v169 offset:16384
	ds_read_b128 v[192:195], v169 offset:17408
	ds_read_b128 v[196:199], v169 offset:18432
	ds_read_b128 v[200:203], v169 offset:19456
	ds_read_b128 v[204:207], v169 offset:20480
	ds_read_b128 v[210:213], v169 offset:21504
	ds_read_b128 v[214:217], v169 offset:22528
	ds_read_b128 v[218:221], v169 offset:23552
	global_load_lds_dwordx4 v[164:165], off
	s_add_i32 m0, s52, 0x2000
	s_add_u32 s52, s74, 0x40000
	v_lshl_add_u64 v[222:223], s[74:75], 0, v[134:135]
	s_addc_u32 s53, s75, 0
	s_add_i32 s78, s89, s61
	global_load_lds_dwordx4 v[222:223], off
	v_lshl_add_u64 v[224:225], s[52:53], 0, v[130:131]
	s_mov_b32 m0, s78
	v_lshl_add_u64 v[226:227], s[76:77], 0, v[132:133]
	global_load_lds_dwordx4 v[224:225], off
	v_lshl_add_u64 v[224:225], s[52:53], 0, v[134:135]
	s_add_i32 m0, s78, 0x2000
	s_nop 0
	global_load_lds_dwordx4 v[224:225], off
	v_lshl_add_u64 v[224:225], s[76:77], 0, v[128:129]
	s_mov_b32 m0, s81
	s_nop 0
	global_load_lds_dwordx4 v[224:225], off
	s_mov_b32 m0, s82
	s_nop 0
	global_load_lds_dwordx4 v[226:227], off
	s_waitcnt vmcnt(8)
	s_waitcnt lgkmcnt(0)
	s_barrier
; #define PG8_STAGE(bufoff, gbase, voff) do { _Pragma("unroll") for (int _i = 0; _i < 2; ++_i) \
;         __builtin_amdgcn_global_load_lds((const unsigned*)((const char*)(gbase) + (voff)[_i]), (PG8_LAS unsigned*)(lds + (bufoff) + ldsw + _i * 8192), 16, 0, 0); } while (0)
; #define PG8_LDA(dst, b, h) do { _Pragma("unroll") for (int m = 0; m < 4; ++m) _Pragma("unroll") for (int k = 0; k < 2; ++k) dst[m][k] = *(const PG8_LAS bf16x8*)(lds + PG8_SA(b, h) + aoff + m * 2048 + k * 1024); } while (0)
; #define PG8_LDB(dst, b, h) do { _Pragma("unroll") for (int n = 0; n < 2; ++n) _Pragma("unroll") for (int k = 0; k < 2; ++k) dst[n][k] = *(const PG8_LAS bf16x8*)(lds + PG8_SB(b, h) + boff + n * 2048 + k * 1024); } while (0)
; #define PG8_MMA(ai, bj, At, Bt) do { __builtin_amdgcn_s_setprio(1); _Pragma("unroll") for (int m = 0; m < 4; ++m) _Pragma("unroll") for (int n = 0; n < 2; ++n) _Pragma("unroll") for (int k = 0; k < 2; ++k) \
;         acc[ai][bj][m][n] = __builtin_amdgcn_mfma_f32_16x16x32_bf16(Bt[n][k], At[m][k], acc[ai][bj][m][n], 0, 0, 0); __builtin_amdgcn_s_setprio(0); } while (0)
; #define PG8_WAIT_V(n) asm volatile("s_waitcnt vmcnt(" #n ")" ::: "memory")
; #define PG8_WAIT_L(n) asm volatile("s_waitcnt lgkmcnt(" #n ")" ::: "memory")
; #define PG8_BAR __builtin_amdgcn_s_barrier()
; #define PG8_SCHED __builtin_amdgcn_sched_barrier(0)
; template <class Epi, class Sched, bool ALIGN_EPI = false, bool SP2 = false>
; __device__ __forceinline__ void gemm_phase(PG8_LAS unsigned char* lds, const Gemm g, const Sched& S, const Epi& E) {
;     ...
;             PG8_WAIT_V(8); PG8_WAIT_L(0); PG8_BAR; PG8_MMA(0, 0, At, B0); PG8_MMA(0, 1, At, B1); PG8_BAR; PG8_SCHED;
;             PG8_LDA(At, 0, 1); PG8_STAGE(PG8_SB(0, 0), b2, voffB); PG8_STAGE(PG8_SB(0, 1), b2 + hstep, voffB); PG8_STAGE(PG8_SA(0, 0), a2, voffA);
;             PG8_WAIT_V(8); PG8_WAIT_L(0); PG8_BAR; PG8_MMA(1, 0, At, B0); PG8_MMA(1, 1, At, B1); PG8_BAR; PG8_SCHED;
;             PG8_LDB(B0, 1, 0); PG8_LDB(B1, 1, 1); PG8_SCHED; PG8_LDA(At, 1, 0); PG8_STAGE(PG8_SA(0, 1), a2 + hstep, voffA);
;             PG8_WAIT_V(8); PG8_WAIT_L(0); PG8_BAR; PG8_MMA(0, 0, At, B0); PG8_MMA(0, 1, At, B1); PG8_BAR; PG8_SCHED;
	s_setprio 1
	s_waitcnt lgkmcnt(0)
	v_mfma_f32_16x16x32_bf16 v[60:63], v[148:151], v[188:191], 0
	v_mfma_f32_16x16x32_bf16 v[56:59], v[156:159], v[188:191], 0
	v_mfma_f32_16x16x32_bf16 v[44:47], v[148:151], v[196:199], 0
	v_mfma_f32_16x16x32_bf16 v[40:43], v[156:159], v[196:199], 0
	v_mfma_f32_16x16x32_bf16 v[28:31], v[148:151], v[204:207], 0
	v_mfma_f32_16x16x32_bf16 v[24:27], v[156:159], v[204:207], 0
	v_mfma_f32_16x16x32_bf16 v[12:15], v[148:151], v[214:217], 0
	v_mfma_f32_16x16x32_bf16 v[8:11], v[156:159], v[214:217], 0
	v_mfma_f32_16x16x32_bf16 v[60:63], v[152:155], v[192:195], v[60:63]
	v_mfma_f32_16x16x32_bf16 v[56:59], v[160:163], v[192:195], v[56:59]
	v_mfma_f32_16x16x32_bf16 v[44:47], v[152:155], v[200:203], v[44:47]
	v_mfma_f32_16x16x32_bf16 v[40:43], v[160:163], v[200:203], v[40:43]
	v_mfma_f32_16x16x32_bf16 v[28:31], v[152:155], v[210:213], v[28:31]
	v_mfma_f32_16x16x32_bf16 v[24:27], v[160:163], v[210:213], v[24:27]
	v_mfma_f32_16x16x32_bf16 v[12:15], v[152:155], v[218:221], v[12:15]
	v_mfma_f32_16x16x32_bf16 v[8:11], v[160:163], v[218:221], v[8:11]
	s_setprio 0
	s_setprio 1
	v_mfma_f32_16x16x32_bf16 v[52:55], v[172:175], v[188:191], 0
	v_mfma_f32_16x16x32_bf16 v[48:51], v[180:183], v[188:191], 0
	v_mfma_f32_16x16x32_bf16 v[36:39], v[172:175], v[196:199], 0
	v_mfma_f32_16x16x32_bf16 v[32:35], v[180:183], v[196:199], 0
	v_mfma_f32_16x16x32_bf16 v[20:23], v[172:175], v[204:207], 0
	v_mfma_f32_16x16x32_bf16 v[16:19], v[180:183], v[204:207], 0
	v_mfma_f32_16x16x32_bf16 v[4:7], v[172:175], v[214:217], 0
	v_mfma_f32_16x16x32_bf16 v[0:3], v[180:183], v[214:217], 0
	v_mfma_f32_16x16x32_bf16 v[52:55], v[176:179], v[192:195], v[52:55]
	v_mfma_f32_16x16x32_bf16 v[48:51], v[184:187], v[192:195], v[48:51]
	v_mfma_f32_16x16x32_bf16 v[36:39], v[176:179], v[200:203], v[36:39]
	v_mfma_f32_16x16x32_bf16 v[32:35], v[184:187], v[200:203], v[32:35]
	v_mfma_f32_16x16x32_bf16 v[20:23], v[176:179], v[210:213], v[20:23]
	v_mfma_f32_16x16x32_bf16 v[16:19], v[184:187], v[210:213], v[16:19]
	v_mfma_f32_16x16x32_bf16 v[4:7], v[176:179], v[218:221], v[4:7]
	s_barrier
	v_mfma_f32_16x16x32_bf16 v[0:3], v[184:187], v[218:221], v[0:3]
	s_setprio 0
	s_add_i32 s78, 0, 0x18000
	v_add_u32_e32 v136, s78, v166
	s_add_i32 s26, 0, 0x1c000
	ds_read_b128 v[148:151], v136
	ds_read_b128 v[152:155], v136 offset:1024
	ds_read_b128 v[156:159], v136 offset:2048
	ds_read_b128 v[160:163], v136 offset:3072
	v_add_u32_e32 v136, s26, v166
	ds_read_b128 v[172:175], v136
	ds_read_b128 v[176:179], v136 offset:1024
	ds_read_b128 v[180:183], v136 offset:2048
	ds_read_b128 v[184:187], v136 offset:3072
	s_add_u32 s52, s76, 0x40000
	s_addc_u32 s53, s77, 0
	s_mov_b32 m0, s83
	v_lshl_add_u64 v[228:229], s[52:53], 0, v[128:129]
	ds_read_b128 v[188:191], v169 offset:32768
	ds_read_b128 v[192:195], v169 offset:33792
	ds_read_b128 v[196:199], v169 offset:34816
	ds_read_b128 v[200:203], v169 offset:35840
	ds_read_b128 v[204:207], v169 offset:36864
	ds_read_b128 v[210:213], v169 offset:37888
	ds_read_b128 v[214:217], v169 offset:38912
	ds_read_b128 v[218:221], v169 offset:39936
	global_load_lds_dwordx4 v[228:229], off
	v_lshl_add_u64 v[228:229], s[52:53], 0, v[132:133]
	s_mov_b32 m0, s84
	s_nop 0
	global_load_lds_dwordx4 v[228:229], off
	s_waitcnt vmcnt(8)
	s_waitcnt lgkmcnt(0)
	s_barrier
	s_setprio 1
	s_waitcnt lgkmcnt(0)
	v_mfma_f32_16x16x32_bf16 v[124:127], v[148:151], v[188:191], v[124:127]
	v_mfma_f32_16x16x32_bf16 v[120:123], v[156:159], v[188:191], v[120:123]
	v_mfma_f32_16x16x32_bf16 v[108:111], v[148:151], v[196:199], v[108:111]
	v_mfma_f32_16x16x32_bf16 v[104:107], v[156:159], v[196:199], v[104:107]
	v_mfma_f32_16x16x32_bf16 v[92:95], v[148:151], v[204:207], v[92:95]
	v_mfma_f32_16x16x32_bf16 v[88:91], v[156:159], v[204:207], v[88:91]
	v_mfma_f32_16x16x32_bf16 v[76:79], v[148:151], v[214:217], v[76:79]
	v_mfma_f32_16x16x32_bf16 v[72:75], v[156:159], v[214:217], v[72:75]
	v_mfma_f32_16x16x32_bf16 v[124:127], v[152:155], v[192:195], v[124:127]
	v_mfma_f32_16x16x32_bf16 v[120:123], v[160:163], v[192:195], v[120:123]
	v_mfma_f32_16x16x32_bf16 v[108:111], v[152:155], v[200:203], v[108:111]
	v_mfma_f32_16x16x32_bf16 v[104:107], v[160:163], v[200:203], v[104:107]
	v_mfma_f32_16x16x32_bf16 v[92:95], v[152:155], v[210:213], v[92:95]
	v_mfma_f32_16x16x32_bf16 v[88:91], v[160:163], v[210:213], v[88:91]
	v_mfma_f32_16x16x32_bf16 v[76:79], v[152:155], v[218:221], v[76:79]
	v_mfma_f32_16x16x32_bf16 v[72:75], v[160:163], v[218:221], v[72:75]
	s_setprio 0
	s_setprio 1
	v_mfma_f32_16x16x32_bf16 v[116:119], v[172:175], v[188:191], v[116:119]
	v_mfma_f32_16x16x32_bf16 v[112:115], v[180:183], v[188:191], v[112:115]
	v_mfma_f32_16x16x32_bf16 v[100:103], v[172:175], v[196:199], v[100:103]
	v_mfma_f32_16x16x32_bf16 v[96:99], v[180:183], v[196:199], v[96:99]
	v_mfma_f32_16x16x32_bf16 v[84:87], v[172:175], v[204:207], v[84:87]
	v_mfma_f32_16x16x32_bf16 v[80:83], v[180:183], v[204:207], v[80:83]
	v_mfma_f32_16x16x32_bf16 v[68:71], v[172:175], v[214:217], v[68:71]
	v_mfma_f32_16x16x32_bf16 v[64:67], v[180:183], v[214:217], v[64:67]
	v_mfma_f32_16x16x32_bf16 v[116:119], v[176:179], v[192:195], v[116:119]
	v_mfma_f32_16x16x32_bf16 v[112:115], v[184:187], v[192:195], v[112:115]
	v_mfma_f32_16x16x32_bf16 v[100:103], v[176:179], v[200:203], v[100:103]
	v_mfma_f32_16x16x32_bf16 v[96:99], v[184:187], v[200:203], v[96:99]
	v_mfma_f32_16x16x32_bf16 v[84:87], v[176:179], v[210:213], v[84:87]
	v_mfma_f32_16x16x32_bf16 v[80:83], v[184:187], v[210:213], v[80:83]
	v_mfma_f32_16x16x32_bf16 v[68:71], v[176:179], v[218:221], v[68:71]
	s_barrier
; #define PG8_STAGE(bufoff, gbase, voff) do { _Pragma("unroll") for (int _i = 0; _i < 2; ++_i) \
;         __builtin_amdgcn_global_load_lds((const unsigned*)((const char*)(gbase) + (voff)[_i]), (PG8_LAS unsigned*)(lds + (bufoff) + ldsw + _i * 8192), 16, 0, 0); } while (0)
; #define PG8_LDA(dst, b, h) do { _Pragma("unroll") for (int m = 0; m < 4; ++m) _Pragma("unroll") for (int k = 0; k < 2; ++k) dst[m][k] = *(const PG8_LAS bf16x8*)(lds + PG8_SA(b, h) + aoff + m * 2048 + k * 1024); } while (0)
; #define PG8_MMA(ai, bj, At, Bt) do { __builtin_amdgcn_s_setprio(1); _Pragma("unroll") for (int m = 0; m < 4; ++m) _Pragma("unroll") for (int n = 0; n < 2; ++n) _Pragma("unroll") for (int k = 0; k < 2; ++k) \
;         acc[ai][bj][m][n] = __builtin_amdgcn_mfma_f32_16x16x32_bf16(Bt[n][k], At[m][k], acc[ai][bj][m][n], 0, 0, 0); __builtin_amdgcn_s_setprio(0); } while (0)
; #define PG8_WAIT_V(n) asm volatile("s_waitcnt vmcnt(" #n ")" ::: "memory")
; #define PG8_WAIT_L(n) asm volatile("s_waitcnt lgkmcnt(" #n ")" ::: "memory")
; #define PG8_BAR __builtin_amdgcn_s_barrier()
; #define PG8_SCHED __builtin_amdgcn_sched_barrier(0)
; template <class Epi, class Sched, bool ALIGN_EPI = false, bool SP2 = false>
; __device__ __forceinline__ void gemm_phase(PG8_LAS unsigned char* lds, const Gemm g, const Sched& S, const Epi& E) {
;     ...
;         for (int t = 0; t < nt; t += 2) {
;     ...
;             PG8_WAIT_V(8); PG8_WAIT_L(0); PG8_BAR; PG8_MMA(0, 0, At, B0); PG8_MMA(0, 1, At, B1); PG8_BAR; PG8_SCHED;
;             PG8_LDA(At, 1, 1); PG8_STAGE(PG8_SB(1, 0), b3, voffB); PG8_STAGE(PG8_SB(1, 1), b3 + hstep, voffB); PG8_STAGE(PG8_SA(1, 0), a3, voffA);
;             PG8_WAIT_V(8); PG8_WAIT_L(0); PG8_BAR; PG8_MMA(1, 0, At, B0); PG8_MMA(1, 1, At, B1); PG8_BAR; PG8_SCHED;
	v_mfma_f32_16x16x32_bf16 v[64:67], v[184:187], v[218:221], v[64:67]
	s_setprio 0
	s_add_i32 s27, s78, s61
	v_lshl_add_u64 v[164:165], v[164:165], 0, s[34:35]
	s_mov_b32 m0, s27
	ds_read_b128 v[188:191], v169 offset:49152
	ds_read_b128 v[192:195], v169 offset:50176
	ds_read_b128 v[196:199], v169 offset:51200
	ds_read_b128 v[200:203], v169 offset:52224
	ds_read_b128 v[204:207], v169 offset:53248
	ds_read_b128 v[210:213], v169 offset:54272
	ds_read_b128 v[214:217], v169 offset:55296
	ds_read_b128 v[218:221], v169 offset:56320
	global_load_lds_dwordx4 v[164:165], off
	s_add_i32 m0, s27, 0x2000
	s_add_u32 s52, s74, 0x40080
	v_lshl_add_u64 v[164:165], v[222:223], 0, s[34:35]
	s_addc_u32 s53, s75, 0
	s_add_i32 s26, s26, s61
	global_load_lds_dwordx4 v[164:165], off
	v_lshl_add_u64 v[164:165], s[52:53], 0, v[130:131]
	s_mov_b32 m0, s26
	s_nop 0
	global_load_lds_dwordx4 v[164:165], off
	v_lshl_add_u64 v[164:165], s[52:53], 0, v[134:135]
	s_add_i32 m0, s26, 0x2000
	s_nop 0
	global_load_lds_dwordx4 v[164:165], off
	v_lshl_add_u64 v[164:165], v[224:225], 0, s[34:35]
	s_mov_b32 m0, s86
	s_nop 0
	global_load_lds_dwordx4 v[164:165], off
	v_lshl_add_u64 v[164:165], v[226:227], 0, s[34:35]
	s_mov_b32 m0, s87
	s_nop 0
	global_load_lds_dwordx4 v[164:165], off
	s_waitcnt vmcnt(8)
	s_waitcnt lgkmcnt(0)
	s_barrier
	s_setprio 1
	s_waitcnt lgkmcnt(0)
	v_mfma_f32_16x16x32_bf16 v[60:63], v[148:151], v[188:191], v[60:63]
	v_mfma_f32_16x16x32_bf16 v[56:59], v[156:159], v[188:191], v[56:59]
	v_mfma_f32_16x16x32_bf16 v[44:47], v[148:151], v[196:199], v[44:47]
	v_mfma_f32_16x16x32_bf16 v[40:43], v[156:159], v[196:199], v[40:43]
	v_mfma_f32_16x16x32_bf16 v[28:31], v[148:151], v[204:207], v[28:31]
	v_mfma_f32_16x16x32_bf16 v[24:27], v[156:159], v[204:207], v[24:27]
	v_mfma_f32_16x16x32_bf16 v[12:15], v[148:151], v[214:217], v[12:15]
	v_mfma_f32_16x16x32_bf16 v[8:11], v[156:159], v[214:217], v[8:11]
	v_mfma_f32_16x16x32_bf16 v[60:63], v[152:155], v[192:195], v[60:63]
	v_mfma_f32_16x16x32_bf16 v[56:59], v[160:163], v[192:195], v[56:59]
	v_mfma_f32_16x16x32_bf16 v[44:47], v[152:155], v[200:203], v[44:47]
	v_mfma_f32_16x16x32_bf16 v[40:43], v[160:163], v[200:203], v[40:43]
	v_mfma_f32_16x16x32_bf16 v[28:31], v[152:155], v[210:213], v[28:31]
	v_mfma_f32_16x16x32_bf16 v[24:27], v[160:163], v[210:213], v[24:27]
	v_mfma_f32_16x16x32_bf16 v[12:15], v[152:155], v[218:221], v[12:15]
	v_mfma_f32_16x16x32_bf16 v[8:11], v[160:163], v[218:221], v[8:11]
	s_setprio 0
	s_setprio 1
	v_mfma_f32_16x16x32_bf16 v[52:55], v[172:175], v[188:191], v[52:55]
	v_mfma_f32_16x16x32_bf16 v[48:51], v[180:183], v[188:191], v[48:51]
	v_mfma_f32_16x16x32_bf16 v[36:39], v[172:175], v[196:199], v[36:39]
	v_mfma_f32_16x16x32_bf16 v[32:35], v[180:183], v[196:199], v[32:35]
	v_mfma_f32_16x16x32_bf16 v[20:23], v[172:175], v[204:207], v[20:23]
	v_mfma_f32_16x16x32_bf16 v[16:19], v[180:183], v[204:207], v[16:19]
	v_mfma_f32_16x16x32_bf16 v[4:7], v[172:175], v[214:217], v[4:7]
	v_mfma_f32_16x16x32_bf16 v[0:3], v[180:183], v[214:217], v[0:3]
	v_mfma_f32_16x16x32_bf16 v[52:55], v[176:179], v[192:195], v[52:55]
	v_mfma_f32_16x16x32_bf16 v[48:51], v[184:187], v[192:195], v[48:51]
	v_mfma_f32_16x16x32_bf16 v[36:39], v[176:179], v[200:203], v[36:39]
	v_mfma_f32_16x16x32_bf16 v[32:35], v[184:187], v[200:203], v[32:35]
	v_mfma_f32_16x16x32_bf16 v[20:23], v[176:179], v[210:213], v[20:23]
	v_mfma_f32_16x16x32_bf16 v[16:19], v[184:187], v[210:213], v[16:19]
	v_mfma_f32_16x16x32_bf16 v[4:7], v[176:179], v[218:221], v[4:7]
	s_barrier
	v_mfma_f32_16x16x32_bf16 v[0:3], v[184:187], v[218:221], v[0:3]
	s_setprio 0
	s_add_i32 vcc_hi, vcc_hi, 2
	s_add_u32 s72, s72, 0x100
	s_addc_u32 s73, s73, 0
	s_add_u32 s67, s67, 0x100
	s_addc_u32 vcc_lo, vcc_lo, 0
	s_cmp_gt_u32 vcc_hi, 13

; #define PG8_STAGE(bufoff, gbase, voff) do { _Pragma("unroll") for (int _i = 0; _i < 2; ++_i) \
;         __builtin_amdgcn_global_load_lds((const unsigned*)((const char*)(gbase) + (voff)[_i]), (PG8_LAS unsigned*)(lds + (bufoff) + ldsw + _i * 8192), 16, 0, 0); } while (0)
; #define PG8_LDA(dst, b, h) do { _Pragma("unroll") for (int m = 0; m < 4; ++m) _Pragma("unroll") for (int k = 0; k < 2; ++k) dst[m][k] = *(const PG8_LAS bf16x8*)(lds + PG8_SA(b, h) + aoff + m * 2048 + k * 1024); } while (0)
; #define PG8_LDB(dst, b, h) do { _Pragma("unroll") for (int n = 0; n < 2; ++n) _Pragma("unroll") for (int k = 0; k < 2; ++k) dst[n][k] = *(const PG8_LAS bf16x8*)(lds + PG8_SB(b, h) + boff + n * 2048 + k * 1024); } while (0)
; #define PG8_WAIT_V(n) asm volatile("s_waitcnt vmcnt(" #n ")" ::: "memory")
; #define PG8_WAIT_L(n) asm volatile("s_waitcnt lgkmcnt(" #n ")" ::: "memory")
; #define PG8_BAR __builtin_amdgcn_s_barrier()
; #define PG8_SCHED __builtin_amdgcn_sched_barrier(0)
; template <class Epi, class Sched, bool ALIGN_EPI = false, bool SP2 = false>
; __device__ __forceinline__ void gemm_phase(PG8_LAS unsigned char* lds, const Gemm g, const Sched& S, const Epi& E) {
;     ...
;         const bool has_next = S.next(ui + 1, nxt);
;         const char* nA = has_next ? (const char*)g.A + (size_t)nxt.pm * tstep : cA; const char* nB = has_next ? (const char*)g.Bt + (size_t)nxt.pn * tstep : cB;
;         for (int t = 0; t < nt; t += 2) {
;             const bool last = (t == nt - 2);
;             const char* a1 = cA + (size_t)(t + 1) * kstep;
;             const char* a2 = last ? nA : cA + (size_t)(t + 2) * kstep; const char* b2 = last ? nB : cB + (size_t)(t + 2) * kstep;
;             const char* a3 = a2 + kstep; const char* b3 = b2 + kstep;
;             if (last && has_next) S.a_ready(nxt);
;             if constexpr (SP2) {
;             PG8_LDB(B0, 0, 0); PG8_LDB(B1, 0, 1); PG8_SCHED; PG8_LDA(At, 0, 0); PG8_STAGE(PG8_SA(1, 1), a1 + hstep, voffA);
;             PG8_WAIT_V(8); PG8_WAIT_L(0); PG8_BAR; PG8_MMA(0, 0, At, B0); PG8_MMA(0, 1, At, B1); PG8_BAR; PG8_SCHED;
;             PG8_LDA(At, 0, 1); PG8_STAGE(PG8_SB(0, 0), b2, voffB); PG8_STAGE(PG8_SB(0, 1), b2 + hstep, voffB); PG8_STAGE(PG8_SA(0, 0), a2, voffA);
;             PG8_WAIT_V(8); PG8_WAIT_L(0); PG8_BAR; PG8_MMA(1, 0, At, B0); PG8_MMA(1, 1, At, B1); PG8_BAR; PG8_SCHED;
.LBB0_1270:
	s_ashr_i32 s27, s26, 31
	s_lshl_b64 s[28:29], s[26:27], 19
	s_add_u32 s28, s54, s28
	s_addc_u32 s29, s55, s29
	s_and_b64 s[30:31], s[4:5], exec
	s_cselect_b32 s27, s29, s35
	s_cselect_b32 s80, s28, s34
	s_ashr_i32 s25, s24, 31
	s_lshl_b64 s[30:31], s[24:25], 19
	s_add_u32 s30, s62, s30
	s_addc_u32 s31, s63, s31
	s_and_b64 s[38:39], s[4:5], exec
	s_cselect_b32 s25, s31, s37
	s_cselect_b32 s81, s30, s36
	s_add_u32 s34, s34, 0x40080
	s_addc_u32 s35, s35, 0
	s_add_u32 s82, s36, 0x100
	v_mov_b32_e32 v0, 0
	s_addc_u32 s83, s37, 0
	s_mov_b32 s84, -2
	v_mov_b32_e32 v1, v0
	ds_read_b128 v[144:147], v155
	ds_read_b128 v[148:151], v155 offset:1024
	ds_read_b128 v[160:163], v155 offset:2048
	ds_read_b128 v[164:167], v155 offset:3072
	ds_read_b128 v[168:171], v156
	ds_read_b128 v[172:175], v156 offset:1024
	ds_read_b128 v[176:179], v156 offset:2048
	ds_read_b128 v[180:183], v156 offset:3072
	s_add_u32 s36, s34, 0xfffc0080
	s_addc_u32 s37, s35, -1
	s_cmp_eq_u32 s84, 12
	s_cselect_b32 s39, s27, s37
	s_cselect_b32 s38, s80, s36
	s_cselect_b32 s37, s25, s83
	s_cselect_b32 s36, s81, s82
	v_lshl_add_u64 v[218:219], s[34:35], 0, v[136:137]
	s_add_i32 m0, s67, 0xc000
	ds_read_b128 v[184:187], v157
	ds_read_b128 v[188:191], v157 offset:1024
	ds_read_b128 v[192:195], v157 offset:2048
	ds_read_b128 v[196:199], v157 offset:3072
	ds_read_b128 v[200:203], v157 offset:4096
	ds_read_b128 v[204:207], v157 offset:5120
	ds_read_b128 v[210:213], v157 offset:6144
	ds_read_b128 v[214:217], v157 offset:7168
	global_load_lds_dwordx4 v[218:219], off
	v_lshl_add_u64 v[218:219], s[34:35], 0, v[138:139]
	s_add_i32 m0, s67, 0xe000
	s_nop 0
	global_load_lds_dwordx4 v[218:219], off
	s_waitcnt vmcnt(8)
	s_waitcnt lgkmcnt(0)
	s_barrier
	s_setprio 1
	s_waitcnt lgkmcnt(0)
	v_mfma_f32_16x16x32_bf16 v[124:127], v[144:147], v[184:187], 0
	v_mfma_f32_16x16x32_bf16 v[120:123], v[160:163], v[184:187], 0
	v_mfma_f32_16x16x32_bf16 v[108:111], v[144:147], v[192:195], 0
	v_mfma_f32_16x16x32_bf16 v[104:107], v[160:163], v[192:195], 0
	v_mfma_f32_16x16x32_bf16 v[92:95], v[144:147], v[200:203], 0
	v_mfma_f32_16x16x32_bf16 v[88:91], v[160:163], v[200:203], 0
	v_mfma_f32_16x16x32_bf16 v[76:79], v[144:147], v[210:213], 0
	v_mfma_f32_16x16x32_bf16 v[72:75], v[160:163], v[210:213], 0
	v_mfma_f32_16x16x32_bf16 v[124:127], v[148:151], v[188:191], v[124:127]
	v_mfma_f32_16x16x32_bf16 v[120:123], v[164:167], v[188:191], v[120:123]
	v_mfma_f32_16x16x32_bf16 v[108:111], v[148:151], v[196:199], v[108:111]
	v_mfma_f32_16x16x32_bf16 v[104:107], v[164:167], v[196:199], v[104:107]
	v_mfma_f32_16x16x32_bf16 v[92:95], v[148:151], v[204:207], v[92:95]
	v_mfma_f32_16x16x32_bf16 v[88:91], v[164:167], v[204:207], v[88:91]
	v_mfma_f32_16x16x32_bf16 v[76:79], v[148:151], v[214:217], v[76:79]
	v_mfma_f32_16x16x32_bf16 v[72:75], v[164:167], v[214:217], v[72:75]
	s_setprio 0
	s_setprio 1
	v_mfma_f32_16x16x32_bf16 v[116:119], v[168:171], v[184:187], 0
	v_mfma_f32_16x16x32_bf16 v[112:115], v[176:179], v[184:187], 0
	v_mfma_f32_16x16x32_bf16 v[100:103], v[168:171], v[192:195], 0
	v_mfma_f32_16x16x32_bf16 v[96:99], v[176:179], v[192:195], 0
	v_mfma_f32_16x16x32_bf16 v[84:87], v[168:171], v[200:203], 0
	v_mfma_f32_16x16x32_bf16 v[80:83], v[176:179], v[200:203], 0
	v_mfma_f32_16x16x32_bf16 v[68:71], v[168:171], v[210:213], 0
	v_mfma_f32_16x16x32_bf16 v[64:67], v[176:179], v[210:213], 0
	v_mfma_f32_16x16x32_bf16 v[116:119], v[172:175], v[188:191], v[116:119]
	v_mfma_f32_16x16x32_bf16 v[112:115], v[180:183], v[188:191], v[112:115]
	v_mfma_f32_16x16x32_bf16 v[100:103], v[172:175], v[196:199], v[100:103]
	v_mfma_f32_16x16x32_bf16 v[96:99], v[180:183], v[196:199], v[96:99]
	v_mfma_f32_16x16x32_bf16 v[84:87], v[172:175], v[204:207], v[84:87]
	v_mfma_f32_16x16x32_bf16 v[80:83], v[180:183], v[204:207], v[80:83]
	v_mfma_f32_16x16x32_bf16 v[68:71], v[172:175], v[214:217], v[68:71]
	s_barrier
	v_mfma_f32_16x16x32_bf16 v[64:67], v[180:183], v[214:217], v[64:67]
	s_setprio 0
	s_add_i32 s52, s75, s64
	v_lshl_add_u64 v[218:219], s[36:37], 0, v[130:131]
	s_mov_b32 m0, s52
	ds_read_b128 v[184:187], v157 offset:16384
	ds_read_b128 v[188:191], v157 offset:17408
	ds_read_b128 v[192:195], v157 offset:18432
	ds_read_b128 v[196:199], v157 offset:19456
	ds_read_b128 v[200:203], v157 offset:20480
	ds_read_b128 v[204:207], v157 offset:21504
	ds_read_b128 v[210:213], v157 offset:22528
	ds_read_b128 v[214:217], v157 offset:23552
	global_load_lds_dwordx4 v[218:219], off
	s_add_i32 m0, s52, 0x2000
	s_add_u32 s52, s36, 0x40000
	v_lshl_add_u64 v[220:221], s[36:37], 0, v[134:135]
	s_addc_u32 s53, s37, 0
	s_add_i32 s78, s76, s64
	global_load_lds_dwordx4 v[220:221], off
	v_lshl_add_u64 v[222:223], s[52:53], 0, v[130:131]
	s_mov_b32 m0, s78
	v_lshl_add_u64 v[224:225], s[38:39], 0, v[132:133]
	global_load_lds_dwordx4 v[222:223], off
	v_lshl_add_u64 v[222:223], s[52:53], 0, v[134:135]
	s_add_i32 m0, s78, 0x2000
	s_nop 0
	global_load_lds_dwordx4 v[222:223], off
	v_lshl_add_u64 v[222:223], s[38:39], 0, v[128:129]
	s_mov_b32 m0, s67
	s_nop 0
	global_load_lds_dwordx4 v[222:223], off
	s_mov_b32 m0, s68
	s_nop 0
	global_load_lds_dwordx4 v[224:225], off
	s_waitcnt vmcnt(8)
	s_waitcnt lgkmcnt(0)
	s_barrier
; #define PG8_STAGE(bufoff, gbase, voff) do { _Pragma("unroll") for (int _i = 0; _i < 2; ++_i) \
;         __builtin_amdgcn_global_load_lds((const unsigned*)((const char*)(gbase) + (voff)[_i]), (PG8_LAS unsigned*)(lds + (bufoff) + ldsw + _i * 8192), 16, 0, 0); } while (0)
; #define PG8_LDA(dst, b, h) do { _Pragma("unroll") for (int m = 0; m < 4; ++m) _Pragma("unroll") for (int k = 0; k < 2; ++k) dst[m][k] = *(const PG8_LAS bf16x8*)(lds + PG8_SA(b, h) + aoff + m * 2048 + k * 1024); } while (0)
; #define PG8_LDB(dst, b, h) do { _Pragma("unroll") for (int n = 0; n < 2; ++n) _Pragma("unroll") for (int k = 0; k < 2; ++k) dst[n][k] = *(const PG8_LAS bf16x8*)(lds + PG8_SB(b, h) + boff + n * 2048 + k * 1024); } while (0)
; #define PG8_MMA(ai, bj, At, Bt) do { __builtin_amdgcn_s_setprio(1); _Pragma("unroll") for (int m = 0; m < 4; ++m) _Pragma("unroll") for (int n = 0; n < 2; ++n) _Pragma("unroll") for (int k = 0; k < 2; ++k) \
;         acc[ai][bj][m][n] = __builtin_amdgcn_mfma_f32_16x16x32_bf16(Bt[n][k], At[m][k], acc[ai][bj][m][n], 0, 0, 0); __builtin_amdgcn_s_setprio(0); } while (0)
; #define PG8_WAIT_V(n) asm volatile("s_waitcnt vmcnt(" #n ")" ::: "memory")
; #define PG8_WAIT_L(n) asm volatile("s_waitcnt lgkmcnt(" #n ")" ::: "memory")
; #define PG8_BAR __builtin_amdgcn_s_barrier()
; #define PG8_SCHED __builtin_amdgcn_sched_barrier(0)
; template <class Epi, class Sched, bool ALIGN_EPI = false, bool SP2 = false>
; __device__ __forceinline__ void gemm_phase(PG8_LAS unsigned char* lds, const Gemm g, const Sched& S, const Epi& E) {
;     ...
;             PG8_WAIT_V(8); PG8_WAIT_L(0); PG8_BAR; PG8_MMA(0, 0, At, B0); PG8_MMA(0, 1, At, B1); PG8_BAR; PG8_SCHED;
;             PG8_LDA(At, 0, 1); PG8_STAGE(PG8_SB(0, 0), b2, voffB); PG8_STAGE(PG8_SB(0, 1), b2 + hstep, voffB); PG8_STAGE(PG8_SA(0, 0), a2, voffA);
;             PG8_WAIT_V(8); PG8_WAIT_L(0); PG8_BAR; PG8_MMA(1, 0, At, B0); PG8_MMA(1, 1, At, B1); PG8_BAR; PG8_SCHED;
;             PG8_LDB(B0, 1, 0); PG8_LDB(B1, 1, 1); PG8_SCHED; PG8_LDA(At, 1, 0); PG8_STAGE(PG8_SA(0, 1), a2 + hstep, voffA);
;             PG8_WAIT_V(8); PG8_WAIT_L(0); PG8_BAR; PG8_MMA(0, 0, At, B0); PG8_MMA(0, 1, At, B1); PG8_BAR; PG8_SCHED;
	s_setprio 1
	s_waitcnt lgkmcnt(0)
	v_mfma_f32_16x16x32_bf16 v[60:63], v[144:147], v[184:187], 0
	v_mfma_f32_16x16x32_bf16 v[56:59], v[160:163], v[184:187], 0
	v_mfma_f32_16x16x32_bf16 v[44:47], v[144:147], v[192:195], 0
	v_mfma_f32_16x16x32_bf16 v[40:43], v[160:163], v[192:195], 0
	v_mfma_f32_16x16x32_bf16 v[28:31], v[144:147], v[200:203], 0
	v_mfma_f32_16x16x32_bf16 v[24:27], v[160:163], v[200:203], 0
	v_mfma_f32_16x16x32_bf16 v[12:15], v[144:147], v[210:213], 0
	v_mfma_f32_16x16x32_bf16 v[8:11], v[160:163], v[210:213], 0
	v_mfma_f32_16x16x32_bf16 v[60:63], v[148:151], v[188:191], v[60:63]
	v_mfma_f32_16x16x32_bf16 v[56:59], v[164:167], v[188:191], v[56:59]
	v_mfma_f32_16x16x32_bf16 v[44:47], v[148:151], v[196:199], v[44:47]
	v_mfma_f32_16x16x32_bf16 v[40:43], v[164:167], v[196:199], v[40:43]
	v_mfma_f32_16x16x32_bf16 v[28:31], v[148:151], v[204:207], v[28:31]
	v_mfma_f32_16x16x32_bf16 v[24:27], v[164:167], v[204:207], v[24:27]
	v_mfma_f32_16x16x32_bf16 v[12:15], v[148:151], v[214:217], v[12:15]
	v_mfma_f32_16x16x32_bf16 v[8:11], v[164:167], v[214:217], v[8:11]
	s_setprio 0
	s_setprio 1
	v_mfma_f32_16x16x32_bf16 v[52:55], v[168:171], v[184:187], 0
	v_mfma_f32_16x16x32_bf16 v[48:51], v[176:179], v[184:187], 0
	v_mfma_f32_16x16x32_bf16 v[36:39], v[168:171], v[192:195], 0
	v_mfma_f32_16x16x32_bf16 v[32:35], v[176:179], v[192:195], 0
	v_mfma_f32_16x16x32_bf16 v[20:23], v[168:171], v[200:203], 0
	v_mfma_f32_16x16x32_bf16 v[16:19], v[176:179], v[200:203], 0
	v_mfma_f32_16x16x32_bf16 v[4:7], v[168:171], v[210:213], 0
	v_mfma_f32_16x16x32_bf16 v[0:3], v[176:179], v[210:213], 0
	v_mfma_f32_16x16x32_bf16 v[52:55], v[172:175], v[188:191], v[52:55]
	v_mfma_f32_16x16x32_bf16 v[48:51], v[180:183], v[188:191], v[48:51]
	v_mfma_f32_16x16x32_bf16 v[36:39], v[172:175], v[196:199], v[36:39]
	v_mfma_f32_16x16x32_bf16 v[32:35], v[180:183], v[196:199], v[32:35]
	v_mfma_f32_16x16x32_bf16 v[20:23], v[172:175], v[204:207], v[20:23]
	v_mfma_f32_16x16x32_bf16 v[16:19], v[180:183], v[204:207], v[16:19]
	v_mfma_f32_16x16x32_bf16 v[4:7], v[172:175], v[214:217], v[4:7]
	s_barrier
	v_mfma_f32_16x16x32_bf16 v[0:3], v[180:183], v[214:217], v[0:3]
	s_setprio 0
	s_add_i32 s52, 0, 0x18000
	v_add_u32_e32 v159, s52, v153
	s_add_i32 s53, 0, 0x1c000
	ds_read_b128 v[144:147], v159
	ds_read_b128 v[148:151], v159 offset:1024
	ds_read_b128 v[160:163], v159 offset:2048
	ds_read_b128 v[164:167], v159 offset:3072
	v_add_u32_e32 v159, s53, v153
	ds_read_b128 v[168:171], v159
	ds_read_b128 v[172:175], v159 offset:1024
	ds_read_b128 v[176:179], v159 offset:2048
	ds_read_b128 v[180:183], v159 offset:3072
	s_add_u32 s38, s38, 0x40000
	s_addc_u32 s39, s39, 0
	s_mov_b32 m0, s69
	v_lshl_add_u64 v[226:227], s[38:39], 0, v[128:129]
	ds_read_b128 v[184:187], v157 offset:32768
	ds_read_b128 v[188:191], v157 offset:33792
	ds_read_b128 v[192:195], v157 offset:34816
	ds_read_b128 v[196:199], v157 offset:35840
	ds_read_b128 v[200:203], v157 offset:36864
	ds_read_b128 v[204:207], v157 offset:37888
	ds_read_b128 v[210:213], v157 offset:38912
	ds_read_b128 v[214:217], v157 offset:39936
	global_load_lds_dwordx4 v[226:227], off
	v_lshl_add_u64 v[226:227], s[38:39], 0, v[132:133]
	s_mov_b32 m0, s70
	s_nop 0
	global_load_lds_dwordx4 v[226:227], off
	s_waitcnt vmcnt(8)
	s_waitcnt lgkmcnt(0)
	s_barrier
	s_setprio 1
	s_waitcnt lgkmcnt(0)
	v_mfma_f32_16x16x32_bf16 v[124:127], v[144:147], v[184:187], v[124:127]
	v_mfma_f32_16x16x32_bf16 v[120:123], v[160:163], v[184:187], v[120:123]
	v_mfma_f32_16x16x32_bf16 v[108:111], v[144:147], v[192:195], v[108:111]
	v_mfma_f32_16x16x32_bf16 v[104:107], v[160:163], v[192:195], v[104:107]
	v_mfma_f32_16x16x32_bf16 v[92:95], v[144:147], v[200:203], v[92:95]
	v_mfma_f32_16x16x32_bf16 v[88:91], v[160:163], v[200:203], v[88:91]
	v_mfma_f32_16x16x32_bf16 v[76:79], v[144:147], v[210:213], v[76:79]
	v_mfma_f32_16x16x32_bf16 v[72:75], v[160:163], v[210:213], v[72:75]
	v_mfma_f32_16x16x32_bf16 v[124:127], v[148:151], v[188:191], v[124:127]
	v_mfma_f32_16x16x32_bf16 v[120:123], v[164:167], v[188:191], v[120:123]
	v_mfma_f32_16x16x32_bf16 v[108:111], v[148:151], v[196:199], v[108:111]
	v_mfma_f32_16x16x32_bf16 v[104:107], v[164:167], v[196:199], v[104:107]
	v_mfma_f32_16x16x32_bf16 v[92:95], v[148:151], v[204:207], v[92:95]
	v_mfma_f32_16x16x32_bf16 v[88:91], v[164:167], v[204:207], v[88:91]
	v_mfma_f32_16x16x32_bf16 v[76:79], v[148:151], v[214:217], v[76:79]
	v_mfma_f32_16x16x32_bf16 v[72:75], v[164:167], v[214:217], v[72:75]
	s_setprio 0
	s_setprio 1
	v_mfma_f32_16x16x32_bf16 v[116:119], v[168:171], v[184:187], v[116:119]
	v_mfma_f32_16x16x32_bf16 v[112:115], v[176:179], v[184:187], v[112:115]
	v_mfma_f32_16x16x32_bf16 v[100:103], v[168:171], v[192:195], v[100:103]
	v_mfma_f32_16x16x32_bf16 v[96:99], v[176:179], v[192:195], v[96:99]
	v_mfma_f32_16x16x32_bf16 v[84:87], v[168:171], v[200:203], v[84:87]
	v_mfma_f32_16x16x32_bf16 v[80:83], v[176:179], v[200:203], v[80:83]
	v_mfma_f32_16x16x32_bf16 v[68:71], v[168:171], v[210:213], v[68:71]
	v_mfma_f32_16x16x32_bf16 v[64:67], v[176:179], v[210:213], v[64:67]
	v_mfma_f32_16x16x32_bf16 v[116:119], v[172:175], v[188:191], v[116:119]
	v_mfma_f32_16x16x32_bf16 v[112:115], v[180:183], v[188:191], v[112:115]
	v_mfma_f32_16x16x32_bf16 v[100:103], v[172:175], v[196:199], v[100:103]
	v_mfma_f32_16x16x32_bf16 v[96:99], v[180:183], v[196:199], v[96:99]
	v_mfma_f32_16x16x32_bf16 v[84:87], v[172:175], v[204:207], v[84:87]
	v_mfma_f32_16x16x32_bf16 v[80:83], v[180:183], v[204:207], v[80:83]
	v_mfma_f32_16x16x32_bf16 v[68:71], v[172:175], v[214:217], v[68:71]
	s_barrier
; #define PG8_STAGE(bufoff, gbase, voff) do { _Pragma("unroll") for (int _i = 0; _i < 2; ++_i) \
;         __builtin_amdgcn_global_load_lds((const unsigned*)((const char*)(gbase) + (voff)[_i]), (PG8_LAS unsigned*)(lds + (bufoff) + ldsw + _i * 8192), 16, 0, 0); } while (0)
; #define PG8_LDA(dst, b, h) do { _Pragma("unroll") for (int m = 0; m < 4; ++m) _Pragma("unroll") for (int k = 0; k < 2; ++k) dst[m][k] = *(const PG8_LAS bf16x8*)(lds + PG8_SA(b, h) + aoff + m * 2048 + k * 1024); } while (0)
; #define PG8_MMA(ai, bj, At, Bt) do { __builtin_amdgcn_s_setprio(1); _Pragma("unroll") for (int m = 0; m < 4; ++m) _Pragma("unroll") for (int n = 0; n < 2; ++n) _Pragma("unroll") for (int k = 0; k < 2; ++k) \
;         acc[ai][bj][m][n] = __builtin_amdgcn_mfma_f32_16x16x32_bf16(Bt[n][k], At[m][k], acc[ai][bj][m][n], 0, 0, 0); __builtin_amdgcn_s_setprio(0); } while (0)
; #define PG8_WAIT_V(n) asm volatile("s_waitcnt vmcnt(" #n ")" ::: "memory")
; #define PG8_WAIT_L(n) asm volatile("s_waitcnt lgkmcnt(" #n ")" ::: "memory")
; #define PG8_BAR __builtin_amdgcn_s_barrier()
; #define PG8_SCHED __builtin_amdgcn_sched_barrier(0)
; template <class Epi, class Sched, bool ALIGN_EPI = false, bool SP2 = false>
; __device__ __forceinline__ void gemm_phase(PG8_LAS unsigned char* lds, const Gemm g, const Sched& S, const Epi& E) {
;     ...
;         for (int t = 0; t < nt; t += 2) {
;     ...
;             PG8_WAIT_V(8); PG8_WAIT_L(0); PG8_BAR; PG8_MMA(0, 0, At, B0); PG8_MMA(0, 1, At, B1); PG8_BAR; PG8_SCHED;
;             PG8_LDA(At, 1, 1); PG8_STAGE(PG8_SB(1, 0), b3, voffB); PG8_STAGE(PG8_SB(1, 1), b3 + hstep, voffB); PG8_STAGE(PG8_SA(1, 0), a3, voffA);
;             PG8_WAIT_V(8); PG8_WAIT_L(0); PG8_BAR; PG8_MMA(1, 0, At, B0); PG8_MMA(1, 1, At, B1); PG8_BAR; PG8_SCHED;
	v_mfma_f32_16x16x32_bf16 v[64:67], v[180:183], v[214:217], v[64:67]
	s_setprio 0
	s_add_i32 s38, s52, s64
	v_lshl_add_u64 v[218:219], v[218:219], 0, s[16:17]
	s_mov_b32 m0, s38
	ds_read_b128 v[184:187], v157 offset:49152
	ds_read_b128 v[188:191], v157 offset:50176
	ds_read_b128 v[192:195], v157 offset:51200
	ds_read_b128 v[196:199], v157 offset:52224
	ds_read_b128 v[200:203], v157 offset:53248
	ds_read_b128 v[204:207], v157 offset:54272
	ds_read_b128 v[210:213], v157 offset:55296
	ds_read_b128 v[214:217], v157 offset:56320
	global_load_lds_dwordx4 v[218:219], off
	s_add_i32 m0, s38, 0x2000
	s_add_u32 s36, s36, 0x40080
	v_lshl_add_u64 v[218:219], v[220:221], 0, s[16:17]
	s_addc_u32 s37, s37, 0
	s_add_i32 s38, s53, s64
	global_load_lds_dwordx4 v[218:219], off
	v_lshl_add_u64 v[218:219], s[36:37], 0, v[130:131]
	s_mov_b32 m0, s38
	s_nop 0
	global_load_lds_dwordx4 v[218:219], off
	v_lshl_add_u64 v[218:219], s[36:37], 0, v[134:135]
	s_add_i32 m0, s38, 0x2000
	s_nop 0
	global_load_lds_dwordx4 v[218:219], off
	v_lshl_add_u64 v[218:219], v[222:223], 0, s[16:17]
	s_mov_b32 m0, s72
	s_nop 0
	global_load_lds_dwordx4 v[218:219], off
	v_lshl_add_u64 v[218:219], v[224:225], 0, s[16:17]
	s_mov_b32 m0, s73
	s_nop 0
	global_load_lds_dwordx4 v[218:219], off
	s_waitcnt vmcnt(8)
	s_waitcnt lgkmcnt(0)
	s_barrier
	s_setprio 1
	s_waitcnt lgkmcnt(0)
	v_mfma_f32_16x16x32_bf16 v[60:63], v[144:147], v[184:187], v[60:63]
	v_mfma_f32_16x16x32_bf16 v[56:59], v[160:163], v[184:187], v[56:59]
	v_mfma_f32_16x16x32_bf16 v[44:47], v[144:147], v[192:195], v[44:47]
	v_mfma_f32_16x16x32_bf16 v[40:43], v[160:163], v[192:195], v[40:43]
	v_mfma_f32_16x16x32_bf16 v[28:31], v[144:147], v[200:203], v[28:31]
	v_mfma_f32_16x16x32_bf16 v[24:27], v[160:163], v[200:203], v[24:27]
	v_mfma_f32_16x16x32_bf16 v[12:15], v[144:147], v[210:213], v[12:15]
	v_mfma_f32_16x16x32_bf16 v[8:11], v[160:163], v[210:213], v[8:11]
	v_mfma_f32_16x16x32_bf16 v[60:63], v[148:151], v[188:191], v[60:63]
	v_mfma_f32_16x16x32_bf16 v[56:59], v[164:167], v[188:191], v[56:59]
	v_mfma_f32_16x16x32_bf16 v[44:47], v[148:151], v[196:199], v[44:47]
	v_mfma_f32_16x16x32_bf16 v[40:43], v[164:167], v[196:199], v[40:43]
	v_mfma_f32_16x16x32_bf16 v[28:31], v[148:151], v[204:207], v[28:31]
	v_mfma_f32_16x16x32_bf16 v[24:27], v[164:167], v[204:207], v[24:27]
	v_mfma_f32_16x16x32_bf16 v[12:15], v[148:151], v[214:217], v[12:15]
	v_mfma_f32_16x16x32_bf16 v[8:11], v[164:167], v[214:217], v[8:11]
	s_setprio 0
	s_setprio 1
	v_mfma_f32_16x16x32_bf16 v[52:55], v[168:171], v[184:187], v[52:55]
	v_mfma_f32_16x16x32_bf16 v[48:51], v[176:179], v[184:187], v[48:51]
	v_mfma_f32_16x16x32_bf16 v[36:39], v[168:171], v[192:195], v[36:39]
	v_mfma_f32_16x16x32_bf16 v[32:35], v[176:179], v[192:195], v[32:35]
	v_mfma_f32_16x16x32_bf16 v[20:23], v[168:171], v[200:203], v[20:23]
	v_mfma_f32_16x16x32_bf16 v[16:19], v[176:179], v[200:203], v[16:19]
	v_mfma_f32_16x16x32_bf16 v[4:7], v[168:171], v[210:213], v[4:7]
	v_mfma_f32_16x16x32_bf16 v[0:3], v[176:179], v[210:213], v[0:3]
	v_mfma_f32_16x16x32_bf16 v[52:55], v[172:175], v[188:191], v[52:55]
	v_mfma_f32_16x16x32_bf16 v[48:51], v[180:183], v[188:191], v[48:51]
	v_mfma_f32_16x16x32_bf16 v[36:39], v[172:175], v[196:199], v[36:39]
	v_mfma_f32_16x16x32_bf16 v[32:35], v[180:183], v[196:199], v[32:35]
	v_mfma_f32_16x16x32_bf16 v[20:23], v[172:175], v[204:207], v[20:23]
	v_mfma_f32_16x16x32_bf16 v[16:19], v[180:183], v[204:207], v[16:19]
	v_mfma_f32_16x16x32_bf16 v[4:7], v[172:175], v[214:217], v[4:7]
	s_barrier
	v_mfma_f32_16x16x32_bf16 v[0:3], v[180:183], v[214:217], v[0:3]
	s_setprio 0
	s_add_i32 s84, s84, 2
	s_add_u32 s34, s34, 0x100
	s_addc_u32 s35, s35, 0
	s_add_u32 s82, s82, 0x100
	s_addc_u32 s83, s83, 0
	s_cmp_gt_u32 s84, 13
